# v9: softmax scale folded into q before its bf16 rounding (q/k post phase) and the shift dropped (shift-invariant, bounded scores): 16 fewer VALU per tile in the attention loop
# speedup vs baseline: 1.0560x; 1.0157x over previous
; __device__ __forceinline__ float sum16(float v) { v += __shfl_xor(v, 1); v += __shfl_xor(v, 2); v += __shfl_xor(v, 4); v += __shfl_xor(v, 8); return v; }
; __device__ __forceinline__ v4u qk_chunk(v4u x, const float* w8, const float* c8, const float* s8, bool lat, float sg) {
;     float v[8] = {bflo(x.x), bfhi(x.x), bflo(x.y), bfhi(x.y), bflo(x.z), bfhi(x.z), bflo(x.w), bfhi(x.w)};
;     float ss = 0.f;
; #pragma unroll
;     for (int i = 0; i < 8; ++i) ss += v[i] * v[i];
;     const float rstd = rsqrtf(sum16(ss) * (1.f / 128.f) + EPS);
; #pragma unroll
;     for (int i = 0; i < 8; ++i) v[i] = v[i] * rstd * w8[i];
;     if (lat) {
; #pragma unroll
;         for (int i = 0; i < 8; ++i) { const float pv = __shfl_xor(v[i], 4); v[i] = v[i] * c8[i] + sg * pv * s8[i]; }
; __device__ __forceinline__ void ph_qk_post(const Args& a) {
;     ...
;     for (int item = gw; item < 2 * 32 * 1040; item += NGW) {
;         const int which = item / (32 * 1040), rem = item % (32 * 1040), blk = rem / 1040, it = rem % 1040, m = blk & 1;
;         if (which == 0 && it >= 1024) continue;
;         bf16* base = (which ? KD : QD) + ((size_t)blk * TB + (size_t)it * 16) * 128 + lane * 8;
;         const float* wsrc = (which ? a.in[I_DKN] : a.in[I_DQN]) + m * 128 + l16 * 8;
;         float w8[8];
; #pragma unroll
;         for (int i = 0; i < 8; ++i) w8[i] = wsrc[i];
;         v4u x[4];
; #pragma unroll
;         for (int j = 0; j < 4; ++j) x[j] = *(const v4u*)(base + j * 512);
;         const bool lat = it < 1024;
; #pragma unroll
;         for (int j = 0; j < 4; ++j) {
;             float c8[8], s8[8];
;             if (lat) { const int t = it * 16 + 4 * j + (lane >> 4); const int pos = (l16 & 8) ? (t & 63) : (t >> 6);
;                 const float* cp = ropec + pos * 32 + (l16 & 3) * 8; const float* sp = ropes + pos * 32 + (l16 & 3) * 8;
; #pragma unroll
;                 for (int i = 0; i < 8; ++i) { c8[i] = cp[i]; s8[i] = sp[i]; } }
;             else {
; #pragma unroll
;                 for (int i = 0; i < 8; ++i) { c8[i] = 1.f; s8[i] = 0.f; } }
;             *(v4u*)(base + j * 512) = qk_chunk(x[j], w8, c8, s8, lat, sg);
;         }
.LBB0_931:
	v_mul_hi_i32 v0, v58, s15
	v_lshrrev_b32_e32 v1, 31, v0
	v_ashrrev_i32_e32 v0, 14, v0
	v_add_u32_e32 v0, v0, v1
	v_mul_i32_i24_e32 v0, 0x8200, v0
	v_sub_u32_e32 v1, v58, v0
	v_mul_hi_i32 v0, v1, s15
	v_lshrrev_b32_e32 v2, 31, v0
	v_ashrrev_i32_e32 v0, 9, v0
	v_add_u32_e32 v0, v0, v2
	v_mul_i32_i24_e32 v2, 0x410, v0
	s_waitcnt vmcnt(0)
	v_sub_u32_e32 v20, v1, v2
	v_add_u32_e32 v1, 0x81ff, v58
	v_cmp_lt_u32_e64 s[4:5], s17, v1
	v_cmp_gt_i32_e64 s[6:7], s18, v20
	v_cmp_gt_u32_e64 s[0:1], s16, v1
	s_or_b64 s[2:3], s[4:5], s[6:7]
	s_and_saveexec_b64 s[6:7], s[2:3]
	s_cbranch_execz .LBB0_930
	v_cndmask_b32_e64 v42, v61, v62, s[0:1]
	v_mul_i32_i24_e32 v4, 0x4100, v0
	v_ashrrev_i32_e32 v21, 31, v20
	v_lshl_add_u64 v[2:3], s[68:69], 0, v[42:43]
	v_ashrrev_i32_e32 v5, 31, v4
	v_lshlrev_b64 v[6:7], 12, v[20:21]
	v_lshl_add_u64 v[2:3], v[2:3], 0, v[6:7]
	v_lshlrev_b64 v[4:5], 8, v[4:5]
	v_lshl_add_u64 v[8:9], v[2:3], 0, v[4:5]
	v_mov_b32_e32 v1, s59
	v_mov_b32_e32 v2, s57
	v_cndmask_b32_e64 v3, v1, v2, s[0:1]
	v_mov_b32_e32 v1, s58
	v_mov_b32_e32 v2, s56
	v_lshlrev_b32_e32 v0, 9, v0
	v_cndmask_b32_e64 v2, v1, v2, s[0:1]
	v_mov_b32_e32 v80, 1.0
	v_mov_b32_e32 v81, 0x3e0293ee
	v_cndmask_b32_e64 v80, v80, v81, s[0:1]
	v_and_b32_e32 v42, 0x200, v0
	v_lshl_add_u64 v[0:1], v[2:3], 0, v[42:43]
	v_mov_b32_e32 v49, v43
	v_mov_b32_e32 v51, v43
	v_lshl_add_u64 v[10:11], v[0:1], 0, v[48:49]
	v_lshl_add_u64 v[52:53], v[8:9], 0, v[50:51]
	global_load_dwordx4 v[0:3], v[10:11], off offset:16
	global_load_dwordx4 v[4:7], v[10:11], off
	global_load_dwordx4 v[36:39], v[52:53], off
	global_load_dwordx4 v[16:19], v[52:53], off offset:1024
	global_load_dwordx4 v[12:15], v[52:53], off offset:2048
	s_nop 0
	global_load_dwordx4 v[8:11], v[52:53], off offset:3072
	v_lshlrev_b32_e32 v21, 4, v20
	v_cmp_gt_i32_e64 s[0:1], s18, v20
	v_and_or_b32 v49, v21, 48, v59
	v_ashrrev_i32_e32 v51, 2, v20
	v_mov_b32_e32 v20, 1.0
	v_mov_b32_e32 v32, 0
	v_mov_b32_e32 v33, 0
	v_mov_b32_e32 v34, 0
	v_mov_b32_e32 v35, 0
	v_mov_b32_e32 v28, 0
	v_mov_b32_e32 v29, 0
	v_mov_b32_e32 v30, 0
	v_mov_b32_e32 v31, 0
	v_mov_b32_e32 v21, 1.0
	v_mov_b32_e32 v22, 1.0
	v_mov_b32_e32 v23, 1.0
	v_mov_b32_e32 v24, 1.0
	v_mov_b32_e32 v25, 1.0
	v_mov_b32_e32 v26, 1.0
	v_mov_b32_e32 v27, 1.0
	s_and_saveexec_b64 s[4:5], s[0:1]
	s_cbranch_execz .LBB0_934
	v_cndmask_b32_e32 v20, v49, v51, vcc
	v_lshlrev_b32_e32 v20, 5, v20
	v_ashrrev_i32_e32 v21, 31, v20
	v_lshlrev_b64 v[20:21], 2, v[20:21]
	v_lshl_add_u64 v[54:55], v[44:45], 0, v[20:21]
	v_lshl_add_u64 v[56:57], v[46:47], 0, v[20:21]
	global_load_dwordx4 v[20:23], v[54:55], off
	global_load_dwordx4 v[24:27], v[54:55], off offset:16
	global_load_dwordx4 v[32:35], v[56:57], off
	global_load_dwordx4 v[28:31], v[56:57], off offset:16
.LBB0_934:
	s_or_b64 exec, exec, s[4:5]
	v_and_b32_e32 v54, 64, v63
	v_xor_b32_e32 v42, 1, v63
	v_add_u32_e32 v74, 64, v54
	v_cmp_lt_i32_e64 s[4:5], v42, v74
	s_waitcnt vmcnt(0)
	v_mul_f32_e32 v0, v80, v0
	v_mul_f32_e32 v1, v80, v1
	v_mul_f32_e32 v2, v80, v2
	v_mul_f32_e32 v3, v80, v3
	v_mul_f32_e32 v4, v80, v4
	v_mul_f32_e32 v5, v80, v5
	v_mul_f32_e32 v6, v80, v6
	v_mul_f32_e32 v7, v80, v7
	v_lshlrev_b32_e32 v54, 16, v36
	v_and_b32_e32 v55, 0xffff0000, v36
	v_cndmask_b32_e64 v42, v63, v42, s[4:5]
	v_pk_mul_f32 v[56:57], v[54:55], v[54:55]
	v_lshlrev_b32_e32 v68, 16, v37
	v_and_b32_e32 v69, 0xffff0000, v37
	v_lshlrev_b32_e32 v64, 2, v42
	v_pk_mul_f32 v[36:37], v[68:69], v[68:69]
	v_add_f32_e32 v42, v56, v57
	v_lshlrev_b32_e32 v70, 16, v38
	v_and_b32_e32 v71, 0xffff0000, v38
	v_add_f32_e32 v36, v36, v42
	v_pk_mul_f32 v[66:67], v[70:71], v[70:71]
	v_add_f32_e32 v36, v37, v36
	v_lshlrev_b32_e32 v72, 16, v39
	v_and_b32_e32 v73, 0xffff0000, v39
	v_add_f32_e32 v36, v66, v36
	v_pk_mul_f32 v[38:39], v[72:73], v[72:73]
	v_add_f32_e32 v36, v67, v36
	v_add_f32_e32 v36, v38, v36
	v_add_f32_e32 v36, v39, v36
	ds_bpermute_b32 v37, v64, v36
	v_xor_b32_e32 v38, 2, v63
	v_cmp_lt_i32_e64 s[4:5], v38, v74
	s_waitcnt lgkmcnt(0)
	v_add_f32_e32 v36, v36, v37
	v_cndmask_b32_e64 v38, v63, v38, s[4:5]
	v_lshlrev_b32_e32 v65, 2, v38
	ds_bpermute_b32 v37, v65, v36
	v_xor_b32_e32 v38, 4, v63
	v_cmp_lt_i32_e64 s[4:5], v38, v74
	s_waitcnt lgkmcnt(0)
	v_add_f32_e32 v36, v36, v37
	v_cndmask_b32_e64 v38, v63, v38, s[4:5]
	v_lshlrev_b32_e32 v42, 2, v38
	ds_bpermute_b32 v37, v42, v36
	v_xor_b32_e32 v38, 8, v63
	v_cmp_lt_i32_e64 s[4:5], v38, v74
	s_waitcnt lgkmcnt(0)
	v_add_f32_e32 v36, v36, v37
	v_cndmask_b32_e64 v38, v63, v38, s[4:5]
	v_lshlrev_b32_e32 v66, 2, v38
	ds_bpermute_b32 v37, v66, v36
	s_waitcnt lgkmcnt(0)
	v_add_f32_e32 v36, v36, v37
	v_fmamk_f32 v36, v36, 0x3c000000, v60
	v_mul_f32_e32 v37, 0x4b800000, v36
	v_cmp_gt_f32_e64 s[4:5], s19, v36
	s_nop 1
	v_cndmask_b32_e64 v36, v36, v37, s[4:5]
	v_rsq_f32_e32 v36, v36
	s_nop 0
	v_mul_f32_e32 v37, 0x45800000, v36
	v_cndmask_b32_e64 v56, v36, v37, s[4:5]
	v_pk_mul_f32 v[36:37], v[56:57], v[54:55] op_sel_hi:[0,1]
	v_pk_mul_f32 v[38:39], v[56:57], v[68:69] op_sel_hi:[0,1]
	v_pk_mul_f32 v[54:55], v[56:57], v[70:71] op_sel_hi:[0,1]
	v_pk_mul_f32 v[56:57], v[56:57], v[72:73] op_sel_hi:[0,1]
	v_pk_mul_f32 v[36:37], v[4:5], v[36:37]
	v_pk_mul_f32 v[38:39], v[6:7], v[38:39]
	v_pk_mul_f32 v[54:55], v[0:1], v[54:55]
	v_pk_mul_f32 v[56:57], v[2:3], v[56:57]
	s_and_saveexec_b64 s[4:5], s[0:1]
	s_cbranch_execz .LBB0_936
	ds_bpermute_b32 v68, v42, v36
	ds_bpermute_b32 v69, v42, v37
	ds_bpermute_b32 v70, v42, v38
	ds_bpermute_b32 v71, v42, v39
	ds_bpermute_b32 v72, v42, v54
	ds_bpermute_b32 v73, v42, v55
	s_waitcnt lgkmcnt(4)
	v_pk_mul_f32 v[68:69], v[40:41], v[68:69]
	ds_bpermute_b32 v67, v42, v56
	v_pk_mul_f32 v[32:33], v[32:33], v[68:69]
	s_waitcnt lgkmcnt(3)
	v_pk_mul_f32 v[68:69], v[40:41], v[70:71]
	ds_bpermute_b32 v70, v42, v57
	v_pk_mul_f32 v[34:35], v[34:35], v[68:69]
	s_waitcnt lgkmcnt(2)
	v_pk_mul_f32 v[68:69], v[40:41], v[72:73]
	v_mul_f32_e32 v26, v26, v56
	s_waitcnt lgkmcnt(1)
	v_mul_f32_e32 v56, v40, v67
	v_pk_mul_f32 v[28:29], v[28:29], v[68:69]
	v_mul_f32_e32 v56, v30, v56
	s_waitcnt lgkmcnt(0)
	v_mul_f32_e32 v69, v40, v70
	v_mov_b32_e32 v30, v27
	v_mov_b32_e32 v68, v57
	v_pk_mul_f32 v[30:31], v[30:31], v[68:69]
	v_pk_fma_f32 v[36:37], v[20:21], v[36:37], v[32:33]
	v_mov_b32_e32 v27, v30
	v_mov_b32_e32 v57, v31
	v_pk_fma_f32 v[38:39], v[22:23], v[38:39], v[34:35]
	v_pk_fma_f32 v[54:55], v[24:25], v[54:55], v[28:29]
	v_pk_add_f32 v[56:57], v[26:27], v[56:57]

; #define SBAR() __builtin_amdgcn_sched_barrier(0)
; #define PVR(S, DA, DB, vbase) do { S[0] = tr_read<v_rd_off(DA, 0, 0)>(vbase); S[1] = tr_read<v_rd_off(DA, 0, 1)>(vbase); S[2] = tr_read<v_rd_off(DB, 0, 0)>(vbase); S[3] = tr_read<v_rd_off(DB, 0, 1)>(vbase); \
;     S[4] = tr_read<v_rd_off(DA, 1, 0)>(vbase); S[5] = tr_read<v_rd_off(DA, 1, 1)>(vbase); S[6] = tr_read<v_rd_off(DB, 1, 0)>(vbase); S[7] = tr_read<v_rd_off(DB, 1, 1)>(vbase); } while (0)
; #define RAWBAR() do { asm volatile("s_waitcnt lgkmcnt(0)" ::: "memory"); __builtin_amdgcn_s_barrier(); asm volatile("" ::: "memory"); } while (0)
; #define RAWBAR() do { asm volatile("s_waitcnt lgkmcnt(0)" ::: "memory"); __builtin_amdgcn_s_barrier(); asm volatile("" ::: "memory"); } while (0)
; #define RAWBAR() do { asm volatile("s_waitcnt lgkmcnt(0)" ::: "memory"); __builtin_amdgcn_s_barrier(); asm volatile("" ::: "memory"); } while (0)
; #define RAWBAR() do { asm volatile("s_waitcnt lgkmcnt(0)" ::: "memory"); __builtin_amdgcn_s_barrier(); asm volatile("" ::: "memory"); } while (0)
; #define RAWBAR() do { asm volatile("s_waitcnt lgkmcnt(0)" ::: "memory"); __builtin_amdgcn_s_barrier(); asm volatile("" ::: "memory"); } while (0)
; template <int MODE> ...
;     ...
;   for (int j = 0; j < NT; ++j) {
;     const int buf = j & 1;
;     if (j + 1 < NT) { STAGE((j + 1) * KVBLK, buf ^ 1); }
;     const char* Kb = K_lds + buf * 16384;
;     f32x16 pe = {}, po = {};
; #pragma unroll
;     for (int d0 = 0; d0 < 8; d0 += 2) {
;       const bf16x8 k0 = *reinterpret_cast<const bf16x8*>(Kb + KSWZ(krow, (d0 * 16 + hi * 8) * 2));
;       const bf16x8 k1 = *reinterpret_cast<const bf16x8*>(Kb + KSWZ(krow, ((d0 + 1) * 16 + hi * 8) * 2));
;       pe = __builtin_amdgcn_mfma_f32_32x32x16_bf16(k0, qr[d0], pe, 0, 0, 0);
;       po = __builtin_amdgcn_mfma_f32_32x32x16_bf16(k1, qr[d0 + 1], po, 0, 0, 0); }
;     const int vo = vb0 + buf * 32768;
;     s16x4 R0_[8], R1_[8];
;     PVR(R0_, 0, 1, vo);
;     f32x16 p;
; #pragma unroll
;     for (int r = 0; r < 16; ++r) p[r] = __builtin_amdgcn_exp2f(fmaf(pe[r] + po[r], C, negMc));
;     float ps = 0.f;
; #pragma unroll
;     for (int r = 0; r < 16; ++r) ps += p[r];
;     lsum += ps;
;     const bf16x8 own0 = pk8(p, 0), own1 = pk8(p, 8);
;     SBAR();
;     PV_TAIL4(o, vo, vo + 16384, own0, own1);
;     asm volatile("s_waitcnt vmcnt(0)" ::: "memory");
;     RAWBAR();
;   }
.LBB0_1019:
	ds_read_b128 v[226:229], v225 offset:16384
	ds_read_b128 v[230:233], v223 offset:16384
	ds_read_b128 v[234:237], v222 offset:16384
	ds_read_b128 v[238:241], v221 offset:16384
	s_mov_b32 m0, s24
	s_nop 0
	global_load_lds_dwordx4 v220, s[86:87]
	s_add_i32 m0, s24, 0x2000
	s_nop 0
	global_load_lds_dwordx4 v219, s[86:87]
	v_exp_f32_e32 v144, v144
	v_exp_f32_e32 v145, v145
	v_exp_f32_e32 v146, v146
	v_exp_f32_e32 v147, v147
	s_waitcnt lgkmcnt(2)
	v_mfma_f32_32x32x16_bf16 v[128:143], v[226:229], v[188:191], 0
	v_mfma_f32_32x32x16_bf16 v[128:143], v[230:233], v[184:187], v[128:143]
	ds_read_b128 v[226:229], v225 offset:16512
	ds_read_b128 v[230:233], v223 offset:16512
	v_exp_f32_e32 v148, v148
	v_exp_f32_e32 v149, v149
	v_exp_f32_e32 v150, v150
	v_exp_f32_e32 v151, v151
	v_add_f32_e32 v246, v144, v145
	v_add_f32_e32 v246, v146, v246
	v_add_f32_e32 v246, v147, v246
	s_waitcnt lgkmcnt(2)
	v_mfma_f32_32x32x16_bf16 v[128:143], v[234:237], v[180:183], v[128:143]
	v_mfma_f32_32x32x16_bf16 v[128:143], v[238:241], v[176:179], v[128:143]
	ds_read_b128 v[234:237], v222 offset:16512
	ds_read_b128 v[238:241], v221 offset:16512
	v_exp_f32_e32 v152, v152
	v_exp_f32_e32 v153, v153
	v_exp_f32_e32 v154, v154
	v_exp_f32_e32 v155, v155
	v_add_f32_e32 v246, v148, v246
	v_add_f32_e32 v246, v149, v246
	v_add_f32_e32 v246, v150, v246
	v_add_f32_e32 v246, v151, v246
	s_waitcnt lgkmcnt(2)
	v_mfma_f32_32x32x16_bf16 v[128:143], v[226:229], v[172:175], v[128:143]
	v_mfma_f32_32x32x16_bf16 v[128:143], v[230:233], v[168:171], v[128:143]
	v_exp_f32_e32 v156, v156
	v_exp_f32_e32 v157, v157
	v_exp_f32_e32 v158, v158
	v_exp_f32_e32 v159, v159
	v_add_f32_e32 v246, v152, v246
	v_add_f32_e32 v246, v153, v246
	v_add_f32_e32 v246, v154, v246
	v_add_f32_e32 v246, v155, v246
	v_cvt_pk_bf16_f32 v226, v144, v145
	v_cvt_pk_bf16_f32 v227, v146, v147
	v_cvt_pk_bf16_f32 v228, v148, v149
	v_cvt_pk_bf16_f32 v229, v150, v151
	s_waitcnt lgkmcnt(0)
	v_mfma_f32_32x32x16_bf16 v[128:143], v[234:237], v[164:167], v[128:143]
	v_mfma_f32_32x32x16_bf16 v[128:143], v[238:241], v[160:163], v[128:143]
	v_add_u32_e32 v245, s84, v214
	s_add_i32 s85, s84, 0x8000
	s_cmp_eq_u32 s85, 0x18000
	s_cselect_b32 s85, 0, s85
	ds_read_b64_tr_b16 v[234:235], v245 offset:0
	ds_read_b64_tr_b16 v[236:237], v245 offset:2048
	ds_read_b64_tr_b16 v[238:239], v245 offset:512
	ds_read_b64_tr_b16 v[240:241], v245 offset:2560
	v_permlane32_swap_b32_e32 v226, v228
	v_permlane32_swap_b32_e32 v227, v229
	ds_read_b64_tr_b16 v[144:145], v245 offset:4096
	ds_read_b64_tr_b16 v[146:147], v245 offset:6144
	ds_read_b64_tr_b16 v[148:149], v245 offset:4608
	ds_read_b64_tr_b16 v[150:151], v245 offset:6656
	v_add_f32_e32 v246, v156, v246
	v_add_f32_e32 v246, v157, v246
	v_add_f32_e32 v246, v158, v246
	v_add_f32_e32 v246, v159, v246
	v_cvt_pk_bf16_f32 v230, v152, v153
	v_cvt_pk_bf16_f32 v231, v154, v155
	v_cvt_pk_bf16_f32 v232, v156, v157
	v_cvt_pk_bf16_f32 v233, v158, v159
	v_add_f32_e32 v215, v215, v246
	ds_read_b64_tr_b16 v[152:153], v245 offset:1024
	ds_read_b64_tr_b16 v[154:155], v245 offset:3072
	ds_read_b64_tr_b16 v[156:157], v245 offset:1536
	ds_read_b64_tr_b16 v[158:159], v245 offset:3584
	v_permlane32_swap_b32_e32 v230, v232
	v_permlane32_swap_b32_e32 v231, v233
	s_waitcnt lgkmcnt(8)
	v_mfma_f32_32x32x16_bf16 v[112:127], v[226:229], v[234:237], v[112:127]
	v_mfma_f32_32x32x16_bf16 v[96:111], v[226:229], v[238:241], v[96:111]
	ds_read_b64_tr_b16 v[234:235], v245 offset:5120
	ds_read_b64_tr_b16 v[236:237], v245 offset:7168
	ds_read_b64_tr_b16 v[238:239], v245 offset:5632
	ds_read_b64_tr_b16 v[240:241], v245 offset:7680
	s_add_i32 s41, s85, s24
	s_add_i32 m0, s41, 0x8000
	s_nop 0
	global_load_lds_dwordx4 v218, s[2:3]
	s_waitcnt lgkmcnt(8)
	v_mfma_f32_32x32x16_bf16 v[112:127], v[230:233], v[144:147], v[112:127]
	v_mfma_f32_32x32x16_bf16 v[96:111], v[230:233], v[148:151], v[96:111]
	ds_read_b64_tr_b16 v[144:145], v245 offset:16384
	ds_read_b64_tr_b16 v[146:147], v245 offset:18432
	ds_read_b64_tr_b16 v[148:149], v245 offset:16896
	ds_read_b64_tr_b16 v[150:151], v245 offset:18944
	s_add_i32 s41, s85, s24
	s_add_i32 m0, s41, 0xa000
	s_nop 0
	global_load_lds_dwordx4 v217, s[2:3]
	s_waitcnt lgkmcnt(8)
	v_mfma_f32_32x32x16_bf16 v[80:95], v[226:229], v[152:155], v[80:95]
	v_mfma_f32_32x32x16_bf16 v[64:79], v[226:229], v[156:159], v[64:79]
	ds_read_b64_tr_b16 v[152:153], v245 offset:20480
	ds_read_b64_tr_b16 v[154:155], v245 offset:22528
	ds_read_b64_tr_b16 v[156:157], v245 offset:20992
	ds_read_b64_tr_b16 v[158:159], v245 offset:23040
	s_add_i32 s41, s85, s24
	s_add_i32 m0, s41, 0xc000
	s_nop 0
	global_load_lds_dwordx4 v242, s[2:3]
	s_waitcnt lgkmcnt(8)
	v_mfma_f32_32x32x16_bf16 v[80:95], v[230:233], v[234:237], v[80:95]
	v_mfma_f32_32x32x16_bf16 v[64:79], v[230:233], v[238:241], v[64:79]
	ds_read_b64_tr_b16 v[234:235], v245 offset:17408
	ds_read_b64_tr_b16 v[236:237], v245 offset:19456
	ds_read_b64_tr_b16 v[238:239], v245 offset:17920
	ds_read_b64_tr_b16 v[240:241], v245 offset:19968
	s_add_i32 s41, s85, s24
	s_add_i32 m0, s41, 0xe000
	s_nop 0
	global_load_lds_dwordx4 v243, s[2:3]
	s_waitcnt lgkmcnt(8)
	v_mfma_f32_32x32x16_bf16 v[48:63], v[226:229], v[144:147], v[48:63]
	v_mfma_f32_32x32x16_bf16 v[32:47], v[226:229], v[148:151], v[32:47]
	ds_read_b64_tr_b16 v[144:145], v245 offset:21504
	ds_read_b64_tr_b16 v[146:147], v245 offset:23552
	ds_read_b64_tr_b16 v[148:149], v245 offset:22016
	ds_read_b64_tr_b16 v[150:151], v245 offset:24064
	s_waitcnt lgkmcnt(8)
	v_mfma_f32_32x32x16_bf16 v[48:63], v[230:233], v[152:155], v[48:63]
	v_mfma_f32_32x32x16_bf16 v[32:47], v[230:233], v[156:159], v[32:47]
	s_waitcnt lgkmcnt(0)
	v_mfma_f32_32x32x16_bf16 v[16:31], v[226:229], v[234:237], v[16:31]
	s_waitcnt vmcnt(0)
	s_barrier
; #define SBAR() __builtin_amdgcn_sched_barrier(0)
; #define PVR(S, DA, DB, vbase) do { S[0] = tr_read<v_rd_off(DA, 0, 0)>(vbase); S[1] = tr_read<v_rd_off(DA, 0, 1)>(vbase); S[2] = tr_read<v_rd_off(DB, 0, 0)>(vbase); S[3] = tr_read<v_rd_off(DB, 0, 1)>(vbase); \
;     S[4] = tr_read<v_rd_off(DA, 1, 0)>(vbase); S[5] = tr_read<v_rd_off(DA, 1, 1)>(vbase); S[6] = tr_read<v_rd_off(DB, 1, 0)>(vbase); S[7] = tr_read<v_rd_off(DB, 1, 1)>(vbase); } while (0)
; #define RAWBAR() do { asm volatile("s_waitcnt lgkmcnt(0)" ::: "memory"); __builtin_amdgcn_s_barrier(); asm volatile("" ::: "memory"); } while (0)
; #define RAWBAR() do { asm volatile("s_waitcnt lgkmcnt(0)" ::: "memory"); __builtin_amdgcn_s_barrier(); asm volatile("" ::: "memory"); } while (0)
; #define RAWBAR() do { asm volatile("s_waitcnt lgkmcnt(0)" ::: "memory"); __builtin_amdgcn_s_barrier(); asm volatile("" ::: "memory"); } while (0)
; #define RAWBAR() do { asm volatile("s_waitcnt lgkmcnt(0)" ::: "memory"); __builtin_amdgcn_s_barrier(); asm volatile("" ::: "memory"); } while (0)
; #define RAWBAR() do { asm volatile("s_waitcnt lgkmcnt(0)" ::: "memory"); __builtin_amdgcn_s_barrier(); asm volatile("" ::: "memory"); } while (0)
; template <int MODE> ...
;     ...
;   for (int j = 0; j < NT; ++j) {
;     const int buf = j & 1;
;     if (j + 1 < NT) { STAGE((j + 1) * KVBLK, buf ^ 1); }
;     const char* Kb = K_lds + buf * 16384;
;     f32x16 pe = {}, po = {};
; #pragma unroll
;     for (int d0 = 0; d0 < 8; d0 += 2) {
;       const bf16x8 k0 = *reinterpret_cast<const bf16x8*>(Kb + KSWZ(krow, (d0 * 16 + hi * 8) * 2));
;       const bf16x8 k1 = *reinterpret_cast<const bf16x8*>(Kb + KSWZ(krow, ((d0 + 1) * 16 + hi * 8) * 2));
;       pe = __builtin_amdgcn_mfma_f32_32x32x16_bf16(k0, qr[d0], pe, 0, 0, 0);
;       po = __builtin_amdgcn_mfma_f32_32x32x16_bf16(k1, qr[d0 + 1], po, 0, 0, 0); }
;     const int vo = vb0 + buf * 32768;
;     s16x4 R0_[8], R1_[8];
;     PVR(R0_, 0, 1, vo);
;     f32x16 p;
; #pragma unroll
;     for (int r = 0; r < 16; ++r) p[r] = __builtin_amdgcn_exp2f(fmaf(pe[r] + po[r], C, negMc));
;     float ps = 0.f;
; #pragma unroll
;     for (int r = 0; r < 16; ++r) ps += p[r];
;     lsum += ps;
;     const bf16x8 own0 = pk8(p, 0), own1 = pk8(p, 8);
;     SBAR();
;     PV_TAIL4(o, vo, vo + 16384, own0, own1);
;     asm volatile("s_waitcnt vmcnt(0)" ::: "memory");
;     RAWBAR();
;   }
	s_add_u32 s86, s86, 0x4000
	s_addc_u32 s87, s87, 0
	s_add_u32 s2, s2, 0x8000
	s_addc_u32 s3, s3, 0
	v_mfma_f32_32x32x16_bf16 v[0:15], v[226:229], v[238:241], v[0:15]
	v_mfma_f32_32x32x16_bf16 v[16:31], v[230:233], v[144:147], v[16:31]
	v_mfma_f32_32x32x16_bf16 v[0:15], v[230:233], v[148:151], v[0:15]
	s_add_i32 s84, s84, 0x8000
	s_cmp_eq_u32 s84, 0x18000
	s_cselect_b32 s84, 0, s84
	ds_read_b128 v[226:229], v225 offset:0
	ds_read_b128 v[230:233], v223 offset:0
	ds_read_b128 v[234:237], v222 offset:0
	ds_read_b128 v[238:241], v221 offset:0
	s_add_i32 m0, s24, 0x4000
	s_nop 0
	global_load_lds_dwordx4 v220, s[86:87]
	s_add_i32 m0, s24, 0x6000
	s_nop 0
	global_load_lds_dwordx4 v219, s[86:87]
	v_exp_f32_e32 v128, v128
	v_exp_f32_e32 v129, v129
	v_exp_f32_e32 v130, v130
	v_exp_f32_e32 v131, v131
	s_waitcnt lgkmcnt(2)
	v_mfma_f32_32x32x16_bf16 v[144:159], v[226:229], v[188:191], 0
	v_mfma_f32_32x32x16_bf16 v[144:159], v[230:233], v[184:187], v[144:159]
	ds_read_b128 v[226:229], v225 offset:128
	ds_read_b128 v[230:233], v223 offset:128
	v_exp_f32_e32 v132, v132
	v_exp_f32_e32 v133, v133
	v_exp_f32_e32 v134, v134
	v_exp_f32_e32 v135, v135
	v_add_f32_e32 v246, v128, v129
	v_add_f32_e32 v246, v130, v246
	v_add_f32_e32 v246, v131, v246
	s_waitcnt lgkmcnt(2)
	v_mfma_f32_32x32x16_bf16 v[144:159], v[234:237], v[180:183], v[144:159]
	v_mfma_f32_32x32x16_bf16 v[144:159], v[238:241], v[176:179], v[144:159]
	ds_read_b128 v[234:237], v222 offset:128
	ds_read_b128 v[238:241], v221 offset:128
	v_exp_f32_e32 v136, v136
	v_exp_f32_e32 v137, v137
	v_exp_f32_e32 v138, v138
	v_exp_f32_e32 v139, v139
	v_add_f32_e32 v246, v132, v246
	v_add_f32_e32 v246, v133, v246
	v_add_f32_e32 v246, v134, v246
	v_add_f32_e32 v246, v135, v246
	s_waitcnt lgkmcnt(2)
	v_mfma_f32_32x32x16_bf16 v[144:159], v[226:229], v[172:175], v[144:159]
	v_mfma_f32_32x32x16_bf16 v[144:159], v[230:233], v[168:171], v[144:159]
	v_exp_f32_e32 v140, v140
	v_exp_f32_e32 v141, v141
	v_exp_f32_e32 v142, v142
	v_exp_f32_e32 v143, v143
	v_add_f32_e32 v246, v136, v246
	v_add_f32_e32 v246, v137, v246
	v_add_f32_e32 v246, v138, v246
	v_add_f32_e32 v246, v139, v246
	v_cvt_pk_bf16_f32 v226, v128, v129
	v_cvt_pk_bf16_f32 v227, v130, v131
	v_cvt_pk_bf16_f32 v228, v132, v133
	v_cvt_pk_bf16_f32 v229, v134, v135
	s_waitcnt lgkmcnt(0)
	v_mfma_f32_32x32x16_bf16 v[144:159], v[234:237], v[164:167], v[144:159]
	v_mfma_f32_32x32x16_bf16 v[144:159], v[238:241], v[160:163], v[144:159]
	v_add_u32_e32 v245, s84, v214
	s_add_i32 s85, s84, 0x8000
	s_cmp_eq_u32 s85, 0x18000
	s_cselect_b32 s85, 0, s85
	ds_read_b64_tr_b16 v[234:235], v245 offset:0
	ds_read_b64_tr_b16 v[236:237], v245 offset:2048
	ds_read_b64_tr_b16 v[238:239], v245 offset:512
	ds_read_b64_tr_b16 v[240:241], v245 offset:2560
	v_permlane32_swap_b32_e32 v226, v228
	v_permlane32_swap_b32_e32 v227, v229
	ds_read_b64_tr_b16 v[128:129], v245 offset:4096
	ds_read_b64_tr_b16 v[130:131], v245 offset:6144
	ds_read_b64_tr_b16 v[132:133], v245 offset:4608
	ds_read_b64_tr_b16 v[134:135], v245 offset:6656
	v_add_f32_e32 v246, v140, v246
	v_add_f32_e32 v246, v141, v246
	v_add_f32_e32 v246, v142, v246
	v_add_f32_e32 v246, v143, v246
	v_cvt_pk_bf16_f32 v230, v136, v137
	v_cvt_pk_bf16_f32 v231, v138, v139
	v_cvt_pk_bf16_f32 v232, v140, v141
	v_cvt_pk_bf16_f32 v233, v142, v143
	v_add_f32_e32 v215, v215, v246
	ds_read_b64_tr_b16 v[136:137], v245 offset:1024
	ds_read_b64_tr_b16 v[138:139], v245 offset:3072
	ds_read_b64_tr_b16 v[140:141], v245 offset:1536
	ds_read_b64_tr_b16 v[142:143], v245 offset:3584
	v_permlane32_swap_b32_e32 v230, v232
	v_permlane32_swap_b32_e32 v231, v233
	s_waitcnt lgkmcnt(8)
	v_mfma_f32_32x32x16_bf16 v[112:127], v[226:229], v[234:237], v[112:127]
	v_mfma_f32_32x32x16_bf16 v[96:111], v[226:229], v[238:241], v[96:111]
	ds_read_b64_tr_b16 v[234:235], v245 offset:5120
	ds_read_b64_tr_b16 v[236:237], v245 offset:7168
	ds_read_b64_tr_b16 v[238:239], v245 offset:5632
	ds_read_b64_tr_b16 v[240:241], v245 offset:7680
	s_add_i32 s41, s85, s24
	s_add_i32 m0, s41, 0x8000
	s_nop 0
	global_load_lds_dwordx4 v218, s[2:3]
	s_waitcnt lgkmcnt(8)
	v_mfma_f32_32x32x16_bf16 v[112:127], v[230:233], v[128:131], v[112:127]
	v_mfma_f32_32x32x16_bf16 v[96:111], v[230:233], v[132:135], v[96:111]
	ds_read_b64_tr_b16 v[128:129], v245 offset:16384
	ds_read_b64_tr_b16 v[130:131], v245 offset:18432
	ds_read_b64_tr_b16 v[132:133], v245 offset:16896
	ds_read_b64_tr_b16 v[134:135], v245 offset:18944
	s_add_i32 s41, s85, s24
	s_add_i32 m0, s41, 0xa000
	s_nop 0
	global_load_lds_dwordx4 v217, s[2:3]
	s_waitcnt lgkmcnt(8)
	v_mfma_f32_32x32x16_bf16 v[80:95], v[226:229], v[136:139], v[80:95]
	v_mfma_f32_32x32x16_bf16 v[64:79], v[226:229], v[140:143], v[64:79]
	ds_read_b64_tr_b16 v[136:137], v245 offset:20480
	ds_read_b64_tr_b16 v[138:139], v245 offset:22528
	ds_read_b64_tr_b16 v[140:141], v245 offset:20992
	ds_read_b64_tr_b16 v[142:143], v245 offset:23040
	s_add_i32 s41, s85, s24
	s_add_i32 m0, s41, 0xc000
	s_nop 0
	global_load_lds_dwordx4 v242, s[2:3]
	s_waitcnt lgkmcnt(8)
	v_mfma_f32_32x32x16_bf16 v[80:95], v[230:233], v[234:237], v[80:95]
	v_mfma_f32_32x32x16_bf16 v[64:79], v[230:233], v[238:241], v[64:79]
	ds_read_b64_tr_b16 v[234:235], v245 offset:17408
	ds_read_b64_tr_b16 v[236:237], v245 offset:19456
	ds_read_b64_tr_b16 v[238:239], v245 offset:17920
	ds_read_b64_tr_b16 v[240:241], v245 offset:19968
	s_add_i32 s41, s85, s24
	s_add_i32 m0, s41, 0xe000
	s_nop 0
	global_load_lds_dwordx4 v243, s[2:3]
	s_waitcnt lgkmcnt(8)
	v_mfma_f32_32x32x16_bf16 v[48:63], v[226:229], v[128:131], v[48:63]
	v_mfma_f32_32x32x16_bf16 v[32:47], v[226:229], v[132:135], v[32:47]
	ds_read_b64_tr_b16 v[128:129], v245 offset:21504
	ds_read_b64_tr_b16 v[130:131], v245 offset:23552
	ds_read_b64_tr_b16 v[132:133], v245 offset:22016
	ds_read_b64_tr_b16 v[134:135], v245 offset:24064
	s_waitcnt lgkmcnt(8)
	v_mfma_f32_32x32x16_bf16 v[48:63], v[230:233], v[136:139], v[48:63]
	v_mfma_f32_32x32x16_bf16 v[32:47], v[230:233], v[140:143], v[32:47]
	s_waitcnt lgkmcnt(0)
	v_mfma_f32_32x32x16_bf16 v[16:31], v[226:229], v[234:237], v[16:31]
	s_waitcnt vmcnt(0)
	s_barrier
	s_add_u32 s86, s86, 0x4000
	s_addc_u32 s87, s87, 0
	s_add_u32 s2, s2, 0x8000
	s_addc_u32 s3, s3, 0
	v_mfma_f32_32x32x16_bf16 v[0:15], v[226:229], v[238:241], v[0:15]
	v_mfma_f32_32x32x16_bf16 v[16:31], v[230:233], v[128:131], v[16:31]
	v_mfma_f32_32x32x16_bf16 v[0:15], v[230:233], v[132:135], v[0:15]
	s_add_i32 s84, s84, 0x8000
	s_cmp_eq_u32 s84, 0x18000
	s_cselect_b32 s84, 0, s84
	s_add_i32 s25, s25, 1
	s_cmpk_eq_i32 s25, 0x82
	s_cbranch_scc0 .LBB0_1019
	s_barrier
	s_branch .Lattn_join_m0

; #define SBAR() __builtin_amdgcn_sched_barrier(0)
; #define PVR(S, DA, DB, vbase) do { S[0] = tr_read<v_rd_off(DA, 0, 0)>(vbase); S[1] = tr_read<v_rd_off(DA, 0, 1)>(vbase); S[2] = tr_read<v_rd_off(DB, 0, 0)>(vbase); S[3] = tr_read<v_rd_off(DB, 0, 1)>(vbase); \
;     S[4] = tr_read<v_rd_off(DA, 1, 0)>(vbase); S[5] = tr_read<v_rd_off(DA, 1, 1)>(vbase); S[6] = tr_read<v_rd_off(DB, 1, 0)>(vbase); S[7] = tr_read<v_rd_off(DB, 1, 1)>(vbase); } while (0)
; #define RAWBAR() do { asm volatile("s_waitcnt lgkmcnt(0)" ::: "memory"); __builtin_amdgcn_s_barrier(); asm volatile("" ::: "memory"); } while (0)
; #define RAWBAR() do { asm volatile("s_waitcnt lgkmcnt(0)" ::: "memory"); __builtin_amdgcn_s_barrier(); asm volatile("" ::: "memory"); } while (0)
; #define RAWBAR() do { asm volatile("s_waitcnt lgkmcnt(0)" ::: "memory"); __builtin_amdgcn_s_barrier(); asm volatile("" ::: "memory"); } while (0)
; #define RAWBAR() do { asm volatile("s_waitcnt lgkmcnt(0)" ::: "memory"); __builtin_amdgcn_s_barrier(); asm volatile("" ::: "memory"); } while (0)
; #define RAWBAR() do { asm volatile("s_waitcnt lgkmcnt(0)" ::: "memory"); __builtin_amdgcn_s_barrier(); asm volatile("" ::: "memory"); } while (0)
; template <int MODE> ...
;     ...
;   for (int j = 0; j < NT; ++j) {
;     const int buf = j & 1;
;     if (j + 1 < NT) { STAGE((j + 1) * KVBLK, buf ^ 1); }
;     const char* Kb = K_lds + buf * 16384;
;     f32x16 pe = {}, po = {};
; #pragma unroll
;     for (int d0 = 0; d0 < 8; d0 += 2) {
;       const bf16x8 k0 = *reinterpret_cast<const bf16x8*>(Kb + KSWZ(krow, (d0 * 16 + hi * 8) * 2));
;       const bf16x8 k1 = *reinterpret_cast<const bf16x8*>(Kb + KSWZ(krow, ((d0 + 1) * 16 + hi * 8) * 2));
;       pe = __builtin_amdgcn_mfma_f32_32x32x16_bf16(k0, qr[d0], pe, 0, 0, 0);
;       po = __builtin_amdgcn_mfma_f32_32x32x16_bf16(k1, qr[d0 + 1], po, 0, 0, 0); }
;     const int vo = vb0 + buf * 32768;
;     s16x4 R0_[8], R1_[8];
;     PVR(R0_, 0, 1, vo);
;     f32x16 p;
; #pragma unroll
;     for (int r = 0; r < 16; ++r) p[r] = __builtin_amdgcn_exp2f(fmaf(pe[r] + po[r], C, negMc));
;     float ps = 0.f;
; #pragma unroll
;     for (int r = 0; r < 16; ++r) ps += p[r];
;     lsum += ps;
;     const bf16x8 own0 = pk8(p, 0), own1 = pk8(p, 8);
;     SBAR();
;     PV_TAIL4(o, vo, vo + 16384, own0, own1);
;     asm volatile("s_waitcnt vmcnt(0)" ::: "memory");
;     RAWBAR();
;   }
.LattnB_m0:
	ds_read_b128 v[226:229], v225 offset:16384
	ds_read_b128 v[230:233], v223 offset:16384
	ds_read_b128 v[234:237], v222 offset:16384
	ds_read_b128 v[238:241], v221 offset:16384
	v_exp_f32_e32 v144, v144
	v_exp_f32_e32 v145, v145
	v_exp_f32_e32 v146, v146
	v_exp_f32_e32 v147, v147
	s_waitcnt lgkmcnt(2)
	v_mfma_f32_32x32x16_bf16 v[128:143], v[226:229], v[188:191], 0
	v_mfma_f32_32x32x16_bf16 v[128:143], v[230:233], v[184:187], v[128:143]
	ds_read_b128 v[226:229], v225 offset:16512
	ds_read_b128 v[230:233], v223 offset:16512
	v_exp_f32_e32 v148, v148
	v_exp_f32_e32 v149, v149
	v_exp_f32_e32 v150, v150
	v_exp_f32_e32 v151, v151
	v_add_f32_e32 v246, v144, v145
	v_add_f32_e32 v246, v146, v246
	v_add_f32_e32 v246, v147, v246
	s_waitcnt lgkmcnt(2)
	v_mfma_f32_32x32x16_bf16 v[128:143], v[234:237], v[180:183], v[128:143]
	v_mfma_f32_32x32x16_bf16 v[128:143], v[238:241], v[176:179], v[128:143]
	ds_read_b128 v[234:237], v222 offset:16512
	ds_read_b128 v[238:241], v221 offset:16512
	v_exp_f32_e32 v152, v152
	v_exp_f32_e32 v153, v153
	v_exp_f32_e32 v154, v154
	v_exp_f32_e32 v155, v155
	v_add_f32_e32 v246, v148, v246
	v_add_f32_e32 v246, v149, v246
	v_add_f32_e32 v246, v150, v246
	v_add_f32_e32 v246, v151, v246
	s_waitcnt lgkmcnt(2)
	v_mfma_f32_32x32x16_bf16 v[128:143], v[226:229], v[172:175], v[128:143]
	v_mfma_f32_32x32x16_bf16 v[128:143], v[230:233], v[168:171], v[128:143]
	v_exp_f32_e32 v156, v156
	v_exp_f32_e32 v157, v157
	v_exp_f32_e32 v158, v158
	v_exp_f32_e32 v159, v159
	v_add_f32_e32 v246, v152, v246
	v_add_f32_e32 v246, v153, v246
	v_add_f32_e32 v246, v154, v246
	v_add_f32_e32 v246, v155, v246
	v_cvt_pk_bf16_f32 v226, v144, v145
	v_cvt_pk_bf16_f32 v227, v146, v147
	v_cvt_pk_bf16_f32 v228, v148, v149
	v_cvt_pk_bf16_f32 v229, v150, v151
	s_waitcnt lgkmcnt(0)
	v_mfma_f32_32x32x16_bf16 v[128:143], v[234:237], v[164:167], v[128:143]
	v_mfma_f32_32x32x16_bf16 v[128:143], v[238:241], v[160:163], v[128:143]
	s_waitcnt vmcnt(0)
	s_barrier
	s_add_u32 s86, s86, 0x4000
	s_addc_u32 s87, s87, 0
	s_add_u32 s2, s2, 0x8000
	s_addc_u32 s3, s3, 0
	s_add_i32 m0, s24, 0x4000
	s_nop 0
	global_load_lds_dwordx4 v220, s[86:87]
	s_add_i32 m0, s24, 0x6000
	s_nop 0
	global_load_lds_dwordx4 v219, s[86:87]
	v_add_u32_e32 v245, s84, v214
	s_sub_u32 s85, s84, 0x8000
	s_cmp_eq_u32 s84, 0
	s_cselect_b32 s85, 0x10000, s85
	ds_read_b64_tr_b16 v[234:235], v245 offset:0
	ds_read_b64_tr_b16 v[236:237], v245 offset:2048
	ds_read_b64_tr_b16 v[238:239], v245 offset:512
	ds_read_b64_tr_b16 v[240:241], v245 offset:2560
	v_permlane32_swap_b32_e32 v226, v228
	v_permlane32_swap_b32_e32 v227, v229
	ds_read_b64_tr_b16 v[144:145], v245 offset:4096
	ds_read_b64_tr_b16 v[146:147], v245 offset:6144
	ds_read_b64_tr_b16 v[148:149], v245 offset:4608
	ds_read_b64_tr_b16 v[150:151], v245 offset:6656
	v_add_f32_e32 v246, v156, v246
	v_add_f32_e32 v246, v157, v246
	v_add_f32_e32 v246, v158, v246
	v_add_f32_e32 v246, v159, v246
	v_cvt_pk_bf16_f32 v230, v152, v153
	v_cvt_pk_bf16_f32 v231, v154, v155
	v_cvt_pk_bf16_f32 v232, v156, v157
	v_cvt_pk_bf16_f32 v233, v158, v159
	v_add_f32_e32 v215, v215, v246
	ds_read_b64_tr_b16 v[152:153], v245 offset:1024
	ds_read_b64_tr_b16 v[154:155], v245 offset:3072
	ds_read_b64_tr_b16 v[156:157], v245 offset:1536
	ds_read_b64_tr_b16 v[158:159], v245 offset:3584
	v_permlane32_swap_b32_e32 v230, v232
	v_permlane32_swap_b32_e32 v231, v233
	s_waitcnt lgkmcnt(8)
	v_mfma_f32_32x32x16_bf16 v[112:127], v[226:229], v[234:237], v[112:127]
	v_mfma_f32_32x32x16_bf16 v[96:111], v[226:229], v[238:241], v[96:111]
	ds_read_b64_tr_b16 v[234:235], v245 offset:5120
	ds_read_b64_tr_b16 v[236:237], v245 offset:7168
	ds_read_b64_tr_b16 v[238:239], v245 offset:5632
	ds_read_b64_tr_b16 v[240:241], v245 offset:7680
	s_add_i32 s41, s85, s24
	s_add_i32 m0, s41, 0x8000
	s_nop 0
	global_load_lds_dwordx4 v218, s[2:3]
	s_waitcnt lgkmcnt(8)
	v_mfma_f32_32x32x16_bf16 v[112:127], v[230:233], v[144:147], v[112:127]
	v_mfma_f32_32x32x16_bf16 v[96:111], v[230:233], v[148:151], v[96:111]
	ds_read_b64_tr_b16 v[144:145], v245 offset:16384
	ds_read_b64_tr_b16 v[146:147], v245 offset:18432
	ds_read_b64_tr_b16 v[148:149], v245 offset:16896
	ds_read_b64_tr_b16 v[150:151], v245 offset:18944
	s_add_i32 s41, s85, s24
	s_add_i32 m0, s41, 0xa000
	s_nop 0
	global_load_lds_dwordx4 v217, s[2:3]
	s_waitcnt lgkmcnt(8)
	v_mfma_f32_32x32x16_bf16 v[80:95], v[226:229], v[152:155], v[80:95]
	v_mfma_f32_32x32x16_bf16 v[64:79], v[226:229], v[156:159], v[64:79]
	ds_read_b64_tr_b16 v[152:153], v245 offset:20480
	ds_read_b64_tr_b16 v[154:155], v245 offset:22528
	ds_read_b64_tr_b16 v[156:157], v245 offset:20992
	ds_read_b64_tr_b16 v[158:159], v245 offset:23040
	s_add_i32 s41, s85, s24
	s_add_i32 m0, s41, 0xc000
	s_nop 0
	global_load_lds_dwordx4 v242, s[2:3]
	s_waitcnt lgkmcnt(8)
	v_mfma_f32_32x32x16_bf16 v[80:95], v[230:233], v[234:237], v[80:95]
	v_mfma_f32_32x32x16_bf16 v[64:79], v[230:233], v[238:241], v[64:79]
	ds_read_b64_tr_b16 v[234:235], v245 offset:17408
	ds_read_b64_tr_b16 v[236:237], v245 offset:19456
	ds_read_b64_tr_b16 v[238:239], v245 offset:17920
	ds_read_b64_tr_b16 v[240:241], v245 offset:19968
	s_add_i32 s41, s85, s24
	s_add_i32 m0, s41, 0xe000
	s_nop 0
	global_load_lds_dwordx4 v243, s[2:3]
	s_waitcnt lgkmcnt(8)
	v_mfma_f32_32x32x16_bf16 v[48:63], v[226:229], v[144:147], v[48:63]
	v_mfma_f32_32x32x16_bf16 v[32:47], v[226:229], v[148:151], v[32:47]
	ds_read_b64_tr_b16 v[144:145], v245 offset:21504
	ds_read_b64_tr_b16 v[146:147], v245 offset:23552
	ds_read_b64_tr_b16 v[148:149], v245 offset:22016
	ds_read_b64_tr_b16 v[150:151], v245 offset:24064
	s_waitcnt lgkmcnt(8)
; #define SBAR() __builtin_amdgcn_sched_barrier(0)
; #define PVR(S, DA, DB, vbase) do { S[0] = tr_read<v_rd_off(DA, 0, 0)>(vbase); S[1] = tr_read<v_rd_off(DA, 0, 1)>(vbase); S[2] = tr_read<v_rd_off(DB, 0, 0)>(vbase); S[3] = tr_read<v_rd_off(DB, 0, 1)>(vbase); \
;     S[4] = tr_read<v_rd_off(DA, 1, 0)>(vbase); S[5] = tr_read<v_rd_off(DA, 1, 1)>(vbase); S[6] = tr_read<v_rd_off(DB, 1, 0)>(vbase); S[7] = tr_read<v_rd_off(DB, 1, 1)>(vbase); } while (0)
; #define RAWBAR() do { asm volatile("s_waitcnt lgkmcnt(0)" ::: "memory"); __builtin_amdgcn_s_barrier(); asm volatile("" ::: "memory"); } while (0)
; #define RAWBAR() do { asm volatile("s_waitcnt lgkmcnt(0)" ::: "memory"); __builtin_amdgcn_s_barrier(); asm volatile("" ::: "memory"); } while (0)
; #define RAWBAR() do { asm volatile("s_waitcnt lgkmcnt(0)" ::: "memory"); __builtin_amdgcn_s_barrier(); asm volatile("" ::: "memory"); } while (0)
; #define RAWBAR() do { asm volatile("s_waitcnt lgkmcnt(0)" ::: "memory"); __builtin_amdgcn_s_barrier(); asm volatile("" ::: "memory"); } while (0)
; #define RAWBAR() do { asm volatile("s_waitcnt lgkmcnt(0)" ::: "memory"); __builtin_amdgcn_s_barrier(); asm volatile("" ::: "memory"); } while (0)
; template <int MODE> ...
;     ...
;   for (int j = 0; j < NT; ++j) {
;     const int buf = j & 1;
;     if (j + 1 < NT) { STAGE((j + 1) * KVBLK, buf ^ 1); }
;     const char* Kb = K_lds + buf * 16384;
;     f32x16 pe = {}, po = {};
; #pragma unroll
;     for (int d0 = 0; d0 < 8; d0 += 2) {
;       const bf16x8 k0 = *reinterpret_cast<const bf16x8*>(Kb + KSWZ(krow, (d0 * 16 + hi * 8) * 2));
;       const bf16x8 k1 = *reinterpret_cast<const bf16x8*>(Kb + KSWZ(krow, ((d0 + 1) * 16 + hi * 8) * 2));
;       pe = __builtin_amdgcn_mfma_f32_32x32x16_bf16(k0, qr[d0], pe, 0, 0, 0);
;       po = __builtin_amdgcn_mfma_f32_32x32x16_bf16(k1, qr[d0 + 1], po, 0, 0, 0); }
;     const int vo = vb0 + buf * 32768;
;     s16x4 R0_[8], R1_[8];
;     PVR(R0_, 0, 1, vo);
;     f32x16 p;
; #pragma unroll
;     for (int r = 0; r < 16; ++r) p[r] = __builtin_amdgcn_exp2f(fmaf(pe[r] + po[r], C, negMc));
;     float ps = 0.f;
; #pragma unroll
;     for (int r = 0; r < 16; ++r) ps += p[r];
;     lsum += ps;
;     const bf16x8 own0 = pk8(p, 0), own1 = pk8(p, 8);
;     SBAR();
;     PV_TAIL4(o, vo, vo + 16384, own0, own1);
;     asm volatile("s_waitcnt vmcnt(0)" ::: "memory");
;     RAWBAR();
	v_mfma_f32_32x32x16_bf16 v[48:63], v[230:233], v[152:155], v[48:63]
	v_mfma_f32_32x32x16_bf16 v[32:47], v[230:233], v[156:159], v[32:47]
	s_waitcnt lgkmcnt(0)
	v_mfma_f32_32x32x16_bf16 v[16:31], v[226:229], v[234:237], v[16:31]
	v_mfma_f32_32x32x16_bf16 v[0:15], v[226:229], v[238:241], v[0:15]
	v_mfma_f32_32x32x16_bf16 v[16:31], v[230:233], v[144:147], v[16:31]
	v_mfma_f32_32x32x16_bf16 v[0:15], v[230:233], v[148:151], v[0:15]
	s_add_i32 s84, s84, 0x8000
	s_cmp_eq_u32 s84, 0x18000
	s_cselect_b32 s84, 0, s84
	ds_read_b128 v[226:229], v225 offset:0
	ds_read_b128 v[230:233], v223 offset:0
	ds_read_b128 v[234:237], v222 offset:0
	ds_read_b128 v[238:241], v221 offset:0
	v_exp_f32_e32 v128, v128
	v_exp_f32_e32 v129, v129
	v_exp_f32_e32 v130, v130
	v_exp_f32_e32 v131, v131
	s_waitcnt lgkmcnt(2)
	v_mfma_f32_32x32x16_bf16 v[144:159], v[226:229], v[188:191], 0
	v_mfma_f32_32x32x16_bf16 v[144:159], v[230:233], v[184:187], v[144:159]
	ds_read_b128 v[226:229], v225 offset:128
	ds_read_b128 v[230:233], v223 offset:128
	v_exp_f32_e32 v132, v132
	v_exp_f32_e32 v133, v133
	v_exp_f32_e32 v134, v134
	v_exp_f32_e32 v135, v135
	v_add_f32_e32 v246, v128, v129
	v_add_f32_e32 v246, v130, v246
	v_add_f32_e32 v246, v131, v246
	s_waitcnt lgkmcnt(2)
	v_mfma_f32_32x32x16_bf16 v[144:159], v[234:237], v[180:183], v[144:159]
	v_mfma_f32_32x32x16_bf16 v[144:159], v[238:241], v[176:179], v[144:159]
	ds_read_b128 v[234:237], v222 offset:128
	ds_read_b128 v[238:241], v221 offset:128
	v_exp_f32_e32 v136, v136
	v_exp_f32_e32 v137, v137
	v_exp_f32_e32 v138, v138
	v_exp_f32_e32 v139, v139
	v_add_f32_e32 v246, v132, v246
	v_add_f32_e32 v246, v133, v246
	v_add_f32_e32 v246, v134, v246
	v_add_f32_e32 v246, v135, v246
	s_waitcnt lgkmcnt(2)
	v_mfma_f32_32x32x16_bf16 v[144:159], v[226:229], v[172:175], v[144:159]
	v_mfma_f32_32x32x16_bf16 v[144:159], v[230:233], v[168:171], v[144:159]
	v_exp_f32_e32 v140, v140
	v_exp_f32_e32 v141, v141
	v_exp_f32_e32 v142, v142
	v_exp_f32_e32 v143, v143
	v_add_f32_e32 v246, v136, v246
	v_add_f32_e32 v246, v137, v246
	v_add_f32_e32 v246, v138, v246
	v_add_f32_e32 v246, v139, v246
	v_cvt_pk_bf16_f32 v226, v128, v129
	v_cvt_pk_bf16_f32 v227, v130, v131
	v_cvt_pk_bf16_f32 v228, v132, v133
	v_cvt_pk_bf16_f32 v229, v134, v135
	s_waitcnt lgkmcnt(0)
	v_mfma_f32_32x32x16_bf16 v[144:159], v[234:237], v[164:167], v[144:159]
	v_mfma_f32_32x32x16_bf16 v[144:159], v[238:241], v[160:163], v[144:159]
	s_waitcnt vmcnt(0)
	s_barrier
	s_add_u32 s86, s86, 0x4000
	s_addc_u32 s87, s87, 0
	s_add_u32 s2, s2, 0x8000
	s_addc_u32 s3, s3, 0
	s_mov_b32 m0, s24
	s_nop 0
	global_load_lds_dwordx4 v220, s[86:87]
	s_add_i32 m0, s24, 0x2000
	s_nop 0
	global_load_lds_dwordx4 v219, s[86:87]
	v_add_u32_e32 v245, s84, v214
	s_sub_u32 s85, s84, 0x8000
	s_cmp_eq_u32 s84, 0
	s_cselect_b32 s85, 0x10000, s85
	ds_read_b64_tr_b16 v[234:235], v245 offset:0
	ds_read_b64_tr_b16 v[236:237], v245 offset:2048
	ds_read_b64_tr_b16 v[238:239], v245 offset:512
	ds_read_b64_tr_b16 v[240:241], v245 offset:2560
	v_permlane32_swap_b32_e32 v226, v228
	v_permlane32_swap_b32_e32 v227, v229
	ds_read_b64_tr_b16 v[128:129], v245 offset:4096
	ds_read_b64_tr_b16 v[130:131], v245 offset:6144
	ds_read_b64_tr_b16 v[132:133], v245 offset:4608
	ds_read_b64_tr_b16 v[134:135], v245 offset:6656
	v_add_f32_e32 v246, v140, v246
	v_add_f32_e32 v246, v141, v246
	v_add_f32_e32 v246, v142, v246
	v_add_f32_e32 v246, v143, v246
	v_cvt_pk_bf16_f32 v230, v136, v137
	v_cvt_pk_bf16_f32 v231, v138, v139
	v_cvt_pk_bf16_f32 v232, v140, v141
	v_cvt_pk_bf16_f32 v233, v142, v143
	v_add_f32_e32 v215, v215, v246
	ds_read_b64_tr_b16 v[136:137], v245 offset:1024
	ds_read_b64_tr_b16 v[138:139], v245 offset:3072
	ds_read_b64_tr_b16 v[140:141], v245 offset:1536
	ds_read_b64_tr_b16 v[142:143], v245 offset:3584
	v_permlane32_swap_b32_e32 v230, v232
	v_permlane32_swap_b32_e32 v231, v233
	s_waitcnt lgkmcnt(8)
	v_mfma_f32_32x32x16_bf16 v[112:127], v[226:229], v[234:237], v[112:127]
	v_mfma_f32_32x32x16_bf16 v[96:111], v[226:229], v[238:241], v[96:111]
	ds_read_b64_tr_b16 v[234:235], v245 offset:5120
	ds_read_b64_tr_b16 v[236:237], v245 offset:7168
	ds_read_b64_tr_b16 v[238:239], v245 offset:5632
	ds_read_b64_tr_b16 v[240:241], v245 offset:7680
	s_add_i32 s41, s85, s24
	s_add_i32 m0, s41, 0x8000
	s_nop 0
	global_load_lds_dwordx4 v218, s[2:3]
	s_waitcnt lgkmcnt(8)
	v_mfma_f32_32x32x16_bf16 v[112:127], v[230:233], v[128:131], v[112:127]
	v_mfma_f32_32x32x16_bf16 v[96:111], v[230:233], v[132:135], v[96:111]
	ds_read_b64_tr_b16 v[128:129], v245 offset:16384
	ds_read_b64_tr_b16 v[130:131], v245 offset:18432
	ds_read_b64_tr_b16 v[132:133], v245 offset:16896
	ds_read_b64_tr_b16 v[134:135], v245 offset:18944
	s_add_i32 s41, s85, s24
	s_add_i32 m0, s41, 0xa000
	s_nop 0
	global_load_lds_dwordx4 v217, s[2:3]
	s_waitcnt lgkmcnt(8)
	v_mfma_f32_32x32x16_bf16 v[80:95], v[226:229], v[136:139], v[80:95]
	v_mfma_f32_32x32x16_bf16 v[64:79], v[226:229], v[140:143], v[64:79]
	ds_read_b64_tr_b16 v[136:137], v245 offset:20480
	ds_read_b64_tr_b16 v[138:139], v245 offset:22528
	ds_read_b64_tr_b16 v[140:141], v245 offset:20992
	ds_read_b64_tr_b16 v[142:143], v245 offset:23040
	s_add_i32 s41, s85, s24
	s_add_i32 m0, s41, 0xc000
	s_nop 0
	global_load_lds_dwordx4 v242, s[2:3]
	s_waitcnt lgkmcnt(8)
	v_mfma_f32_32x32x16_bf16 v[80:95], v[230:233], v[234:237], v[80:95]
	v_mfma_f32_32x32x16_bf16 v[64:79], v[230:233], v[238:241], v[64:79]
	ds_read_b64_tr_b16 v[234:235], v245 offset:17408
	ds_read_b64_tr_b16 v[236:237], v245 offset:19456
	ds_read_b64_tr_b16 v[238:239], v245 offset:17920
	ds_read_b64_tr_b16 v[240:241], v245 offset:19968
	s_add_i32 s41, s85, s24
	s_add_i32 m0, s41, 0xe000
	s_nop 0
	global_load_lds_dwordx4 v243, s[2:3]
	s_waitcnt lgkmcnt(8)
	v_mfma_f32_32x32x16_bf16 v[48:63], v[226:229], v[128:131], v[48:63]
	v_mfma_f32_32x32x16_bf16 v[32:47], v[226:229], v[132:135], v[32:47]
	ds_read_b64_tr_b16 v[128:129], v245 offset:21504
	ds_read_b64_tr_b16 v[130:131], v245 offset:23552
	ds_read_b64_tr_b16 v[132:133], v245 offset:22016
	ds_read_b64_tr_b16 v[134:135], v245 offset:24064
	s_waitcnt lgkmcnt(8)
	v_mfma_f32_32x32x16_bf16 v[48:63], v[230:233], v[136:139], v[48:63]
	v_mfma_f32_32x32x16_bf16 v[32:47], v[230:233], v[140:143], v[32:47]
	s_waitcnt lgkmcnt(0)
	v_mfma_f32_32x32x16_bf16 v[16:31], v[226:229], v[234:237], v[16:31]
	v_mfma_f32_32x32x16_bf16 v[0:15], v[226:229], v[238:241], v[0:15]
	v_mfma_f32_32x32x16_bf16 v[16:31], v[230:233], v[128:131], v[16:31]
	v_mfma_f32_32x32x16_bf16 v[0:15], v[230:233], v[132:135], v[0:15]
	s_add_i32 s84, s84, 0x8000
	s_cmp_eq_u32 s84, 0x18000
	s_cselect_b32 s84, 0, s84
	s_add_i32 s25, s25, 1
	s_cmpk_eq_i32 s25, 0x82
	s_cbranch_scc0 .LattnB_m0
	s_waitcnt vmcnt(0)
	s_barrier

; #define SBAR() __builtin_amdgcn_sched_barrier(0)
; #define PVR(S, DA, DB, vbase) do { S[0] = tr_read<v_rd_off(DA, 0, 0)>(vbase); S[1] = tr_read<v_rd_off(DA, 0, 1)>(vbase); S[2] = tr_read<v_rd_off(DB, 0, 0)>(vbase); S[3] = tr_read<v_rd_off(DB, 0, 1)>(vbase); \
;     S[4] = tr_read<v_rd_off(DA, 1, 0)>(vbase); S[5] = tr_read<v_rd_off(DA, 1, 1)>(vbase); S[6] = tr_read<v_rd_off(DB, 1, 0)>(vbase); S[7] = tr_read<v_rd_off(DB, 1, 1)>(vbase); } while (0)
; #define RAWBAR() do { asm volatile("s_waitcnt lgkmcnt(0)" ::: "memory"); __builtin_amdgcn_s_barrier(); asm volatile("" ::: "memory"); } while (0)
; #define RAWBAR() do { asm volatile("s_waitcnt lgkmcnt(0)" ::: "memory"); __builtin_amdgcn_s_barrier(); asm volatile("" ::: "memory"); } while (0)
; #define RAWBAR() do { asm volatile("s_waitcnt lgkmcnt(0)" ::: "memory"); __builtin_amdgcn_s_barrier(); asm volatile("" ::: "memory"); } while (0)
; #define RAWBAR() do { asm volatile("s_waitcnt lgkmcnt(0)" ::: "memory"); __builtin_amdgcn_s_barrier(); asm volatile("" ::: "memory"); } while (0)
; #define RAWBAR() do { asm volatile("s_waitcnt lgkmcnt(0)" ::: "memory"); __builtin_amdgcn_s_barrier(); asm volatile("" ::: "memory"); } while (0)
; template <int MODE> ...
;     ...
;   for (int j = 0; j < NT; ++j) {
;     const int buf = j & 1;
;     if (j + 1 < NT) { STAGE((j + 1) * KVBLK, buf ^ 1); }
;     const char* Kb = K_lds + buf * 16384;
;     f32x16 pe = {}, po = {};
; #pragma unroll
;     for (int d0 = 0; d0 < 8; d0 += 2) {
;       const bf16x8 k0 = *reinterpret_cast<const bf16x8*>(Kb + KSWZ(krow, (d0 * 16 + hi * 8) * 2));
;       const bf16x8 k1 = *reinterpret_cast<const bf16x8*>(Kb + KSWZ(krow, ((d0 + 1) * 16 + hi * 8) * 2));
;       pe = __builtin_amdgcn_mfma_f32_32x32x16_bf16(k0, qr[d0], pe, 0, 0, 0);
;       po = __builtin_amdgcn_mfma_f32_32x32x16_bf16(k1, qr[d0 + 1], po, 0, 0, 0); }
;     const int vo = vb0 + buf * 32768;
;     s16x4 R0_[8], R1_[8];
;     PVR(R0_, 0, 1, vo);
;     f32x16 p;
; #pragma unroll
;     for (int r = 0; r < 16; ++r) p[r] = __builtin_amdgcn_exp2f(fmaf(pe[r] + po[r], C, negMc));
;     float ps = 0.f;
; #pragma unroll
;     for (int r = 0; r < 16; ++r) ps += p[r];
;     lsum += ps;
;     const bf16x8 own0 = pk8(p, 0), own1 = pk8(p, 8);
;     SBAR();
;     PV_TAIL4(o, vo, vo + 16384, own0, own1);
;     asm volatile("s_waitcnt vmcnt(0)" ::: "memory");
;     RAWBAR();
.LBB0_1023:
	ds_read_b128 v[230:233], v229 offset:16384
	ds_read_b128 v[234:237], v228 offset:16384
	ds_read_b128 v[238:241], v227 offset:16384
	ds_read_b128 v[242:245], v226 offset:16384
	s_mov_b32 m0, s34
	s_nop 0
	global_load_lds_dwordx4 v225, s[86:87]
	s_add_i32 m0, s34, 0x2000
	s_nop 0
	global_load_lds_dwordx4 v223, s[86:87]
	v_exp_f32_e32 v144, v144
	v_exp_f32_e32 v145, v145
	v_exp_f32_e32 v146, v146
	v_exp_f32_e32 v147, v147
	s_waitcnt lgkmcnt(2)
	v_mfma_f32_32x32x16_bf16 v[128:143], v[230:233], v[188:191], 0
	v_mfma_f32_32x32x16_bf16 v[128:143], v[234:237], v[184:187], v[128:143]
	ds_read_b128 v[230:233], v229 offset:16512
	ds_read_b128 v[234:237], v228 offset:16512
	v_exp_f32_e32 v148, v148
	v_exp_f32_e32 v149, v149
	v_exp_f32_e32 v150, v150
	v_exp_f32_e32 v151, v151
	v_add_f32_e32 v250, v144, v145
	v_add_f32_e32 v250, v146, v250
	v_add_f32_e32 v250, v147, v250
	s_waitcnt lgkmcnt(2)
	v_mfma_f32_32x32x16_bf16 v[128:143], v[238:241], v[180:183], v[128:143]
	v_mfma_f32_32x32x16_bf16 v[128:143], v[242:245], v[176:179], v[128:143]
	ds_read_b128 v[238:241], v227 offset:16512
	ds_read_b128 v[242:245], v226 offset:16512
	v_exp_f32_e32 v152, v152
	v_exp_f32_e32 v153, v153
	v_exp_f32_e32 v154, v154
	v_exp_f32_e32 v155, v155
	v_add_f32_e32 v250, v148, v250
	v_add_f32_e32 v250, v149, v250
	v_add_f32_e32 v250, v150, v250
	v_add_f32_e32 v250, v151, v250
	s_waitcnt lgkmcnt(2)
	v_mfma_f32_32x32x16_bf16 v[128:143], v[230:233], v[172:175], v[128:143]
	v_mfma_f32_32x32x16_bf16 v[128:143], v[234:237], v[168:171], v[128:143]
	v_exp_f32_e32 v156, v156
	v_exp_f32_e32 v157, v157
	v_exp_f32_e32 v158, v158
	v_exp_f32_e32 v159, v159
	v_add_f32_e32 v250, v152, v250
	v_add_f32_e32 v250, v153, v250
	v_add_f32_e32 v250, v154, v250
	v_add_f32_e32 v250, v155, v250
	v_cvt_pk_bf16_f32 v230, v144, v145
	v_cvt_pk_bf16_f32 v231, v146, v147
	v_cvt_pk_bf16_f32 v232, v148, v149
	v_cvt_pk_bf16_f32 v233, v150, v151
	s_waitcnt lgkmcnt(0)
	v_mfma_f32_32x32x16_bf16 v[128:143], v[238:241], v[164:167], v[128:143]
	v_mfma_f32_32x32x16_bf16 v[128:143], v[242:245], v[160:163], v[128:143]
	v_add_u32_e32 v249, s84, v218
	s_add_i32 s85, s84, 0x8000
	s_cmp_eq_u32 s85, 0x18000
	s_cselect_b32 s85, 0, s85
	ds_read_b64_tr_b16 v[238:239], v249 offset:0
	ds_read_b64_tr_b16 v[240:241], v249 offset:2048
	ds_read_b64_tr_b16 v[242:243], v249 offset:512
	ds_read_b64_tr_b16 v[244:245], v249 offset:2560
	v_permlane32_swap_b32_e32 v230, v232
	v_permlane32_swap_b32_e32 v231, v233
	ds_read_b64_tr_b16 v[144:145], v249 offset:4096
	ds_read_b64_tr_b16 v[146:147], v249 offset:6144
	ds_read_b64_tr_b16 v[148:149], v249 offset:4608
	ds_read_b64_tr_b16 v[150:151], v249 offset:6656
	v_add_f32_e32 v250, v156, v250
	v_add_f32_e32 v250, v157, v250
	v_add_f32_e32 v250, v158, v250
	v_add_f32_e32 v250, v159, v250
	v_cvt_pk_bf16_f32 v234, v152, v153
	v_cvt_pk_bf16_f32 v235, v154, v155
	v_cvt_pk_bf16_f32 v236, v156, v157
	v_cvt_pk_bf16_f32 v237, v158, v159
	v_add_f32_e32 v219, v219, v250
	ds_read_b64_tr_b16 v[152:153], v249 offset:1024
	ds_read_b64_tr_b16 v[154:155], v249 offset:3072
	ds_read_b64_tr_b16 v[156:157], v249 offset:1536
	ds_read_b64_tr_b16 v[158:159], v249 offset:3584
	v_permlane32_swap_b32_e32 v234, v236
	v_permlane32_swap_b32_e32 v235, v237
	s_waitcnt lgkmcnt(8)
	v_mfma_f32_32x32x16_bf16 v[112:127], v[230:233], v[238:241], v[112:127]
	v_mfma_f32_32x32x16_bf16 v[96:111], v[230:233], v[242:245], v[96:111]
	ds_read_b64_tr_b16 v[238:239], v249 offset:5120
	ds_read_b64_tr_b16 v[240:241], v249 offset:7168
	ds_read_b64_tr_b16 v[242:243], v249 offset:5632
	ds_read_b64_tr_b16 v[244:245], v249 offset:7680
	s_add_i32 s30, s85, s34
	s_add_i32 m0, s30, 0x8000
	s_nop 0
	global_load_lds_dwordx4 v222, s[2:3]
	s_waitcnt lgkmcnt(8)
	v_mfma_f32_32x32x16_bf16 v[112:127], v[234:237], v[144:147], v[112:127]
	v_mfma_f32_32x32x16_bf16 v[96:111], v[234:237], v[148:151], v[96:111]
	ds_read_b64_tr_b16 v[144:145], v249 offset:16384
	ds_read_b64_tr_b16 v[146:147], v249 offset:18432
	ds_read_b64_tr_b16 v[148:149], v249 offset:16896
	ds_read_b64_tr_b16 v[150:151], v249 offset:18944
	s_add_i32 s30, s85, s34
	s_add_i32 m0, s30, 0xa000
	s_nop 0
	global_load_lds_dwordx4 v221, s[2:3]
	s_waitcnt lgkmcnt(8)
	v_mfma_f32_32x32x16_bf16 v[80:95], v[230:233], v[152:155], v[80:95]
	v_mfma_f32_32x32x16_bf16 v[64:79], v[230:233], v[156:159], v[64:79]
	ds_read_b64_tr_b16 v[152:153], v249 offset:20480
	ds_read_b64_tr_b16 v[154:155], v249 offset:22528
	ds_read_b64_tr_b16 v[156:157], v249 offset:20992
	ds_read_b64_tr_b16 v[158:159], v249 offset:23040
	s_add_i32 s30, s85, s34
	s_add_i32 m0, s30, 0xc000
	s_nop 0
	global_load_lds_dwordx4 v246, s[2:3]
	s_waitcnt lgkmcnt(8)
	v_mfma_f32_32x32x16_bf16 v[80:95], v[234:237], v[238:241], v[80:95]
	v_mfma_f32_32x32x16_bf16 v[64:79], v[234:237], v[242:245], v[64:79]
	ds_read_b64_tr_b16 v[238:239], v249 offset:17408
	ds_read_b64_tr_b16 v[240:241], v249 offset:19456
	ds_read_b64_tr_b16 v[242:243], v249 offset:17920
	ds_read_b64_tr_b16 v[244:245], v249 offset:19968
	s_add_i32 s30, s85, s34
	s_add_i32 m0, s30, 0xe000
	s_nop 0
	global_load_lds_dwordx4 v247, s[2:3]
	s_waitcnt lgkmcnt(8)
	v_mfma_f32_32x32x16_bf16 v[32:47], v[230:233], v[144:147], v[32:47]
	v_mfma_f32_32x32x16_bf16 v[16:31], v[230:233], v[148:151], v[16:31]
	ds_read_b64_tr_b16 v[144:145], v249 offset:21504
	ds_read_b64_tr_b16 v[146:147], v249 offset:23552
	ds_read_b64_tr_b16 v[148:149], v249 offset:22016
	ds_read_b64_tr_b16 v[150:151], v249 offset:24064
	s_waitcnt lgkmcnt(8)
	v_mfma_f32_32x32x16_bf16 v[32:47], v[234:237], v[152:155], v[32:47]
	v_mfma_f32_32x32x16_bf16 v[16:31], v[234:237], v[156:159], v[16:31]
	s_waitcnt lgkmcnt(0)
	v_mfma_f32_32x32x16_bf16 v[48:63], v[230:233], v[238:241], v[48:63]
	s_waitcnt vmcnt(0)
	s_barrier
; #define SBAR() __builtin_amdgcn_sched_barrier(0)
; #define PVR(S, DA, DB, vbase) do { S[0] = tr_read<v_rd_off(DA, 0, 0)>(vbase); S[1] = tr_read<v_rd_off(DA, 0, 1)>(vbase); S[2] = tr_read<v_rd_off(DB, 0, 0)>(vbase); S[3] = tr_read<v_rd_off(DB, 0, 1)>(vbase); \
;     S[4] = tr_read<v_rd_off(DA, 1, 0)>(vbase); S[5] = tr_read<v_rd_off(DA, 1, 1)>(vbase); S[6] = tr_read<v_rd_off(DB, 1, 0)>(vbase); S[7] = tr_read<v_rd_off(DB, 1, 1)>(vbase); } while (0)
; #define RAWBAR() do { asm volatile("s_waitcnt lgkmcnt(0)" ::: "memory"); __builtin_amdgcn_s_barrier(); asm volatile("" ::: "memory"); } while (0)
; #define RAWBAR() do { asm volatile("s_waitcnt lgkmcnt(0)" ::: "memory"); __builtin_amdgcn_s_barrier(); asm volatile("" ::: "memory"); } while (0)
; #define RAWBAR() do { asm volatile("s_waitcnt lgkmcnt(0)" ::: "memory"); __builtin_amdgcn_s_barrier(); asm volatile("" ::: "memory"); } while (0)
; #define RAWBAR() do { asm volatile("s_waitcnt lgkmcnt(0)" ::: "memory"); __builtin_amdgcn_s_barrier(); asm volatile("" ::: "memory"); } while (0)
; #define RAWBAR() do { asm volatile("s_waitcnt lgkmcnt(0)" ::: "memory"); __builtin_amdgcn_s_barrier(); asm volatile("" ::: "memory"); } while (0)
; template <int MODE> ...
;     ...
;   for (int j = 0; j < NT; ++j) {
;     const int buf = j & 1;
;     if (j + 1 < NT) { STAGE((j + 1) * KVBLK, buf ^ 1); }
;     const char* Kb = K_lds + buf * 16384;
;     f32x16 pe = {}, po = {};
; #pragma unroll
;     for (int d0 = 0; d0 < 8; d0 += 2) {
;       const bf16x8 k0 = *reinterpret_cast<const bf16x8*>(Kb + KSWZ(krow, (d0 * 16 + hi * 8) * 2));
;       const bf16x8 k1 = *reinterpret_cast<const bf16x8*>(Kb + KSWZ(krow, ((d0 + 1) * 16 + hi * 8) * 2));
;       pe = __builtin_amdgcn_mfma_f32_32x32x16_bf16(k0, qr[d0], pe, 0, 0, 0);
;       po = __builtin_amdgcn_mfma_f32_32x32x16_bf16(k1, qr[d0 + 1], po, 0, 0, 0); }
;     const int vo = vb0 + buf * 32768;
;     s16x4 R0_[8], R1_[8];
;     PVR(R0_, 0, 1, vo);
;     f32x16 p;
; #pragma unroll
;     for (int r = 0; r < 16; ++r) p[r] = __builtin_amdgcn_exp2f(fmaf(pe[r] + po[r], C, negMc));
;     float ps = 0.f;
; #pragma unroll
;     for (int r = 0; r < 16; ++r) ps += p[r];
;     lsum += ps;
;     const bf16x8 own0 = pk8(p, 0), own1 = pk8(p, 8);
;     SBAR();
;     PV_TAIL4(o, vo, vo + 16384, own0, own1);
;     asm volatile("s_waitcnt vmcnt(0)" ::: "memory");
;     RAWBAR();
	s_add_u32 s86, s86, 0x4000
	s_addc_u32 s87, s87, 0
	s_add_u32 s2, s2, 0x8000
	s_addc_u32 s3, s3, 0
	v_mfma_f32_32x32x16_bf16 v[0:15], v[230:233], v[242:245], v[0:15]
	v_mfma_f32_32x32x16_bf16 v[48:63], v[234:237], v[144:147], v[48:63]
	v_mfma_f32_32x32x16_bf16 v[0:15], v[234:237], v[148:151], v[0:15]
	s_add_i32 s84, s84, 0x8000
	s_cmp_eq_u32 s84, 0x18000
	s_cselect_b32 s84, 0, s84
	ds_read_b128 v[230:233], v229 offset:0
	ds_read_b128 v[234:237], v228 offset:0
	ds_read_b128 v[238:241], v227 offset:0
	ds_read_b128 v[242:245], v226 offset:0
	s_add_i32 m0, s34, 0x4000
	s_nop 0
	global_load_lds_dwordx4 v225, s[86:87]
	s_add_i32 m0, s34, 0x6000
	s_nop 0
	global_load_lds_dwordx4 v223, s[86:87]
	v_exp_f32_e32 v128, v128
	v_exp_f32_e32 v129, v129
	v_exp_f32_e32 v130, v130
	v_exp_f32_e32 v131, v131
	s_waitcnt lgkmcnt(2)
	v_mfma_f32_32x32x16_bf16 v[144:159], v[230:233], v[188:191], 0
	v_mfma_f32_32x32x16_bf16 v[144:159], v[234:237], v[184:187], v[144:159]
	ds_read_b128 v[230:233], v229 offset:128
	ds_read_b128 v[234:237], v228 offset:128
	v_exp_f32_e32 v132, v132
	v_exp_f32_e32 v133, v133
	v_exp_f32_e32 v134, v134
	v_exp_f32_e32 v135, v135
	v_add_f32_e32 v250, v128, v129
	v_add_f32_e32 v250, v130, v250
	v_add_f32_e32 v250, v131, v250
	s_waitcnt lgkmcnt(2)
	v_mfma_f32_32x32x16_bf16 v[144:159], v[238:241], v[180:183], v[144:159]
	v_mfma_f32_32x32x16_bf16 v[144:159], v[242:245], v[176:179], v[144:159]
	ds_read_b128 v[238:241], v227 offset:128
	ds_read_b128 v[242:245], v226 offset:128
	v_exp_f32_e32 v136, v136
	v_exp_f32_e32 v137, v137
	v_exp_f32_e32 v138, v138
	v_exp_f32_e32 v139, v139
	v_add_f32_e32 v250, v132, v250
	v_add_f32_e32 v250, v133, v250
	v_add_f32_e32 v250, v134, v250
	v_add_f32_e32 v250, v135, v250
	s_waitcnt lgkmcnt(2)
	v_mfma_f32_32x32x16_bf16 v[144:159], v[230:233], v[172:175], v[144:159]
	v_mfma_f32_32x32x16_bf16 v[144:159], v[234:237], v[168:171], v[144:159]
	v_exp_f32_e32 v140, v140
	v_exp_f32_e32 v141, v141
	v_exp_f32_e32 v142, v142
	v_exp_f32_e32 v143, v143
	v_add_f32_e32 v250, v136, v250
	v_add_f32_e32 v250, v137, v250
	v_add_f32_e32 v250, v138, v250
	v_add_f32_e32 v250, v139, v250
	v_cvt_pk_bf16_f32 v230, v128, v129
	v_cvt_pk_bf16_f32 v231, v130, v131
	v_cvt_pk_bf16_f32 v232, v132, v133
	v_cvt_pk_bf16_f32 v233, v134, v135
	s_waitcnt lgkmcnt(0)
	v_mfma_f32_32x32x16_bf16 v[144:159], v[238:241], v[164:167], v[144:159]
	v_mfma_f32_32x32x16_bf16 v[144:159], v[242:245], v[160:163], v[144:159]
	v_add_u32_e32 v249, s84, v218
	s_add_i32 s85, s84, 0x8000
	s_cmp_eq_u32 s85, 0x18000
	s_cselect_b32 s85, 0, s85
	ds_read_b64_tr_b16 v[238:239], v249 offset:0
	ds_read_b64_tr_b16 v[240:241], v249 offset:2048
	ds_read_b64_tr_b16 v[242:243], v249 offset:512
	ds_read_b64_tr_b16 v[244:245], v249 offset:2560
	v_permlane32_swap_b32_e32 v230, v232
	v_permlane32_swap_b32_e32 v231, v233
	ds_read_b64_tr_b16 v[128:129], v249 offset:4096
	ds_read_b64_tr_b16 v[130:131], v249 offset:6144
	ds_read_b64_tr_b16 v[132:133], v249 offset:4608
	ds_read_b64_tr_b16 v[134:135], v249 offset:6656
	v_add_f32_e32 v250, v140, v250
	v_add_f32_e32 v250, v141, v250
	v_add_f32_e32 v250, v142, v250
	v_add_f32_e32 v250, v143, v250
	v_cvt_pk_bf16_f32 v234, v136, v137
	v_cvt_pk_bf16_f32 v235, v138, v139
	v_cvt_pk_bf16_f32 v236, v140, v141
	v_cvt_pk_bf16_f32 v237, v142, v143
	v_add_f32_e32 v219, v219, v250
	ds_read_b64_tr_b16 v[136:137], v249 offset:1024
	ds_read_b64_tr_b16 v[138:139], v249 offset:3072
	ds_read_b64_tr_b16 v[140:141], v249 offset:1536
	ds_read_b64_tr_b16 v[142:143], v249 offset:3584
	v_permlane32_swap_b32_e32 v234, v236
	v_permlane32_swap_b32_e32 v235, v237
	s_waitcnt lgkmcnt(8)
	v_mfma_f32_32x32x16_bf16 v[112:127], v[230:233], v[238:241], v[112:127]
	v_mfma_f32_32x32x16_bf16 v[96:111], v[230:233], v[242:245], v[96:111]
	ds_read_b64_tr_b16 v[238:239], v249 offset:5120
	ds_read_b64_tr_b16 v[240:241], v249 offset:7168
	ds_read_b64_tr_b16 v[242:243], v249 offset:5632
	ds_read_b64_tr_b16 v[244:245], v249 offset:7680
	s_add_i32 s30, s85, s34
	s_add_i32 m0, s30, 0x8000
	s_nop 0
	global_load_lds_dwordx4 v222, s[2:3]
	s_waitcnt lgkmcnt(8)
	v_mfma_f32_32x32x16_bf16 v[112:127], v[234:237], v[128:131], v[112:127]
	v_mfma_f32_32x32x16_bf16 v[96:111], v[234:237], v[132:135], v[96:111]
	ds_read_b64_tr_b16 v[128:129], v249 offset:16384
	ds_read_b64_tr_b16 v[130:131], v249 offset:18432
	ds_read_b64_tr_b16 v[132:133], v249 offset:16896
	ds_read_b64_tr_b16 v[134:135], v249 offset:18944
	s_add_i32 s30, s85, s34
	s_add_i32 m0, s30, 0xa000
	s_nop 0
	global_load_lds_dwordx4 v221, s[2:3]
	s_waitcnt lgkmcnt(8)
	v_mfma_f32_32x32x16_bf16 v[80:95], v[230:233], v[136:139], v[80:95]
	v_mfma_f32_32x32x16_bf16 v[64:79], v[230:233], v[140:143], v[64:79]
	ds_read_b64_tr_b16 v[136:137], v249 offset:20480
	ds_read_b64_tr_b16 v[138:139], v249 offset:22528
	ds_read_b64_tr_b16 v[140:141], v249 offset:20992
	ds_read_b64_tr_b16 v[142:143], v249 offset:23040
	s_add_i32 s30, s85, s34
	s_add_i32 m0, s30, 0xc000
	s_nop 0
	global_load_lds_dwordx4 v246, s[2:3]
	s_waitcnt lgkmcnt(8)
	v_mfma_f32_32x32x16_bf16 v[80:95], v[234:237], v[238:241], v[80:95]
	v_mfma_f32_32x32x16_bf16 v[64:79], v[234:237], v[242:245], v[64:79]
	ds_read_b64_tr_b16 v[238:239], v249 offset:17408
	ds_read_b64_tr_b16 v[240:241], v249 offset:19456
	ds_read_b64_tr_b16 v[242:243], v249 offset:17920
	ds_read_b64_tr_b16 v[244:245], v249 offset:19968
	s_add_i32 s30, s85, s34
	s_add_i32 m0, s30, 0xe000
	s_nop 0
	global_load_lds_dwordx4 v247, s[2:3]
	s_waitcnt lgkmcnt(8)
	v_mfma_f32_32x32x16_bf16 v[32:47], v[230:233], v[128:131], v[32:47]
	v_mfma_f32_32x32x16_bf16 v[16:31], v[230:233], v[132:135], v[16:31]
	ds_read_b64_tr_b16 v[128:129], v249 offset:21504
	ds_read_b64_tr_b16 v[130:131], v249 offset:23552
	ds_read_b64_tr_b16 v[132:133], v249 offset:22016
	ds_read_b64_tr_b16 v[134:135], v249 offset:24064
	s_waitcnt lgkmcnt(8)
	v_mfma_f32_32x32x16_bf16 v[32:47], v[234:237], v[136:139], v[32:47]
	v_mfma_f32_32x32x16_bf16 v[16:31], v[234:237], v[140:143], v[16:31]
	s_waitcnt lgkmcnt(0)
	v_mfma_f32_32x32x16_bf16 v[48:63], v[230:233], v[238:241], v[48:63]
	s_waitcnt vmcnt(0)
	s_barrier
	s_add_u32 s86, s86, 0x4000
	s_addc_u32 s87, s87, 0
	s_add_u32 s2, s2, 0x8000
	s_addc_u32 s3, s3, 0
	v_mfma_f32_32x32x16_bf16 v[0:15], v[230:233], v[242:245], v[0:15]
	v_mfma_f32_32x32x16_bf16 v[48:63], v[234:237], v[128:131], v[48:63]
	v_mfma_f32_32x32x16_bf16 v[0:15], v[234:237], v[132:135], v[0:15]
	s_add_i32 s84, s84, 0x8000
	s_cmp_eq_u32 s84, 0x18000
	s_cselect_b32 s84, 0, s84
	s_add_i32 s40, s40, 1
	s_cmpk_eq_i32 s40, 0x82
	s_cbranch_scc0 .LBB0_1023
	s_barrier
	s_branch .Lattn_join_m1

; #define SBAR() __builtin_amdgcn_sched_barrier(0)
; #define PVR(S, DA, DB, vbase) do { S[0] = tr_read<v_rd_off(DA, 0, 0)>(vbase); S[1] = tr_read<v_rd_off(DA, 0, 1)>(vbase); S[2] = tr_read<v_rd_off(DB, 0, 0)>(vbase); S[3] = tr_read<v_rd_off(DB, 0, 1)>(vbase); \
;     S[4] = tr_read<v_rd_off(DA, 1, 0)>(vbase); S[5] = tr_read<v_rd_off(DA, 1, 1)>(vbase); S[6] = tr_read<v_rd_off(DB, 1, 0)>(vbase); S[7] = tr_read<v_rd_off(DB, 1, 1)>(vbase); } while (0)
; #define RAWBAR() do { asm volatile("s_waitcnt lgkmcnt(0)" ::: "memory"); __builtin_amdgcn_s_barrier(); asm volatile("" ::: "memory"); } while (0)
; #define RAWBAR() do { asm volatile("s_waitcnt lgkmcnt(0)" ::: "memory"); __builtin_amdgcn_s_barrier(); asm volatile("" ::: "memory"); } while (0)
; #define RAWBAR() do { asm volatile("s_waitcnt lgkmcnt(0)" ::: "memory"); __builtin_amdgcn_s_barrier(); asm volatile("" ::: "memory"); } while (0)
; #define RAWBAR() do { asm volatile("s_waitcnt lgkmcnt(0)" ::: "memory"); __builtin_amdgcn_s_barrier(); asm volatile("" ::: "memory"); } while (0)
; #define RAWBAR() do { asm volatile("s_waitcnt lgkmcnt(0)" ::: "memory"); __builtin_amdgcn_s_barrier(); asm volatile("" ::: "memory"); } while (0)
; template <int MODE> ...
;     ...
;   for (int j = 0; j < NT; ++j) {
;     const int buf = j & 1;
;     if (j + 1 < NT) { STAGE((j + 1) * KVBLK, buf ^ 1); }
;     const char* Kb = K_lds + buf * 16384;
;     f32x16 pe = {}, po = {};
; #pragma unroll
;     for (int d0 = 0; d0 < 8; d0 += 2) {
;       const bf16x8 k0 = *reinterpret_cast<const bf16x8*>(Kb + KSWZ(krow, (d0 * 16 + hi * 8) * 2));
;       const bf16x8 k1 = *reinterpret_cast<const bf16x8*>(Kb + KSWZ(krow, ((d0 + 1) * 16 + hi * 8) * 2));
;       pe = __builtin_amdgcn_mfma_f32_32x32x16_bf16(k0, qr[d0], pe, 0, 0, 0);
;       po = __builtin_amdgcn_mfma_f32_32x32x16_bf16(k1, qr[d0 + 1], po, 0, 0, 0); }
;     const int vo = vb0 + buf * 32768;
;     s16x4 R0_[8], R1_[8];
;     PVR(R0_, 0, 1, vo);
;     f32x16 p;
; #pragma unroll
;     for (int r = 0; r < 16; ++r) p[r] = __builtin_amdgcn_exp2f(fmaf(pe[r] + po[r], C, negMc));
;     float ps = 0.f;
; #pragma unroll
;     for (int r = 0; r < 16; ++r) ps += p[r];
;     lsum += ps;
;     const bf16x8 own0 = pk8(p, 0), own1 = pk8(p, 8);
;     SBAR();
;     PV_TAIL4(o, vo, vo + 16384, own0, own1);
;     asm volatile("s_waitcnt vmcnt(0)" ::: "memory");
;     RAWBAR();
.LattnB_m1:
	ds_read_b128 v[230:233], v229 offset:16384
	ds_read_b128 v[234:237], v228 offset:16384
	ds_read_b128 v[238:241], v227 offset:16384
	ds_read_b128 v[242:245], v226 offset:16384
	v_exp_f32_e32 v144, v144
	v_exp_f32_e32 v145, v145
	v_exp_f32_e32 v146, v146
	v_exp_f32_e32 v147, v147
	s_waitcnt lgkmcnt(2)
	v_mfma_f32_32x32x16_bf16 v[128:143], v[230:233], v[188:191], 0
	v_mfma_f32_32x32x16_bf16 v[128:143], v[234:237], v[184:187], v[128:143]
	ds_read_b128 v[230:233], v229 offset:16512
	ds_read_b128 v[234:237], v228 offset:16512
	v_exp_f32_e32 v148, v148
	v_exp_f32_e32 v149, v149
	v_exp_f32_e32 v150, v150
	v_exp_f32_e32 v151, v151
	v_add_f32_e32 v250, v144, v145
	v_add_f32_e32 v250, v146, v250
	v_add_f32_e32 v250, v147, v250
	s_waitcnt lgkmcnt(2)
	v_mfma_f32_32x32x16_bf16 v[128:143], v[238:241], v[180:183], v[128:143]
	v_mfma_f32_32x32x16_bf16 v[128:143], v[242:245], v[176:179], v[128:143]
	ds_read_b128 v[238:241], v227 offset:16512
	ds_read_b128 v[242:245], v226 offset:16512
	v_exp_f32_e32 v152, v152
	v_exp_f32_e32 v153, v153
	v_exp_f32_e32 v154, v154
	v_exp_f32_e32 v155, v155
	v_add_f32_e32 v250, v148, v250
	v_add_f32_e32 v250, v149, v250
	v_add_f32_e32 v250, v150, v250
	v_add_f32_e32 v250, v151, v250
	s_waitcnt lgkmcnt(2)
	v_mfma_f32_32x32x16_bf16 v[128:143], v[230:233], v[172:175], v[128:143]
	v_mfma_f32_32x32x16_bf16 v[128:143], v[234:237], v[168:171], v[128:143]
	v_exp_f32_e32 v156, v156
	v_exp_f32_e32 v157, v157
	v_exp_f32_e32 v158, v158
	v_exp_f32_e32 v159, v159
	v_add_f32_e32 v250, v152, v250
	v_add_f32_e32 v250, v153, v250
	v_add_f32_e32 v250, v154, v250
	v_add_f32_e32 v250, v155, v250
	v_cvt_pk_bf16_f32 v230, v144, v145
	v_cvt_pk_bf16_f32 v231, v146, v147
	v_cvt_pk_bf16_f32 v232, v148, v149
	v_cvt_pk_bf16_f32 v233, v150, v151
	s_waitcnt lgkmcnt(0)
	v_mfma_f32_32x32x16_bf16 v[128:143], v[238:241], v[164:167], v[128:143]
	v_mfma_f32_32x32x16_bf16 v[128:143], v[242:245], v[160:163], v[128:143]
	s_waitcnt vmcnt(0)
	s_barrier
	s_add_u32 s86, s86, 0x4000
	s_addc_u32 s87, s87, 0
	s_add_u32 s2, s2, 0x8000
	s_addc_u32 s3, s3, 0
	s_add_i32 m0, s34, 0x4000
	s_nop 0
	global_load_lds_dwordx4 v225, s[86:87]
	s_add_i32 m0, s34, 0x6000
	s_nop 0
	global_load_lds_dwordx4 v223, s[86:87]
	v_add_u32_e32 v249, s84, v218
	s_sub_u32 s85, s84, 0x8000
	s_cmp_eq_u32 s84, 0
	s_cselect_b32 s85, 0x10000, s85
	ds_read_b64_tr_b16 v[238:239], v249 offset:0
	ds_read_b64_tr_b16 v[240:241], v249 offset:2048
	ds_read_b64_tr_b16 v[242:243], v249 offset:512
	ds_read_b64_tr_b16 v[244:245], v249 offset:2560
	v_permlane32_swap_b32_e32 v230, v232
	v_permlane32_swap_b32_e32 v231, v233
	ds_read_b64_tr_b16 v[144:145], v249 offset:4096
	ds_read_b64_tr_b16 v[146:147], v249 offset:6144
	ds_read_b64_tr_b16 v[148:149], v249 offset:4608
	ds_read_b64_tr_b16 v[150:151], v249 offset:6656
	v_add_f32_e32 v250, v156, v250
	v_add_f32_e32 v250, v157, v250
	v_add_f32_e32 v250, v158, v250
	v_add_f32_e32 v250, v159, v250
	v_cvt_pk_bf16_f32 v234, v152, v153
	v_cvt_pk_bf16_f32 v235, v154, v155
	v_cvt_pk_bf16_f32 v236, v156, v157
	v_cvt_pk_bf16_f32 v237, v158, v159
	v_add_f32_e32 v219, v219, v250
	ds_read_b64_tr_b16 v[152:153], v249 offset:1024
	ds_read_b64_tr_b16 v[154:155], v249 offset:3072
	ds_read_b64_tr_b16 v[156:157], v249 offset:1536
	ds_read_b64_tr_b16 v[158:159], v249 offset:3584
	v_permlane32_swap_b32_e32 v234, v236
	v_permlane32_swap_b32_e32 v235, v237
	s_waitcnt lgkmcnt(8)
	v_mfma_f32_32x32x16_bf16 v[112:127], v[230:233], v[238:241], v[112:127]
	v_mfma_f32_32x32x16_bf16 v[96:111], v[230:233], v[242:245], v[96:111]
	ds_read_b64_tr_b16 v[238:239], v249 offset:5120
	ds_read_b64_tr_b16 v[240:241], v249 offset:7168
	ds_read_b64_tr_b16 v[242:243], v249 offset:5632
	ds_read_b64_tr_b16 v[244:245], v249 offset:7680
	s_add_i32 s30, s85, s34
	s_add_i32 m0, s30, 0x8000
	s_nop 0
	global_load_lds_dwordx4 v222, s[2:3]
	s_waitcnt lgkmcnt(8)
	v_mfma_f32_32x32x16_bf16 v[112:127], v[234:237], v[144:147], v[112:127]
	v_mfma_f32_32x32x16_bf16 v[96:111], v[234:237], v[148:151], v[96:111]
	ds_read_b64_tr_b16 v[144:145], v249 offset:16384
	ds_read_b64_tr_b16 v[146:147], v249 offset:18432
	ds_read_b64_tr_b16 v[148:149], v249 offset:16896
	ds_read_b64_tr_b16 v[150:151], v249 offset:18944
	s_add_i32 s30, s85, s34
	s_add_i32 m0, s30, 0xa000
	s_nop 0
	global_load_lds_dwordx4 v221, s[2:3]
	s_waitcnt lgkmcnt(8)
	v_mfma_f32_32x32x16_bf16 v[80:95], v[230:233], v[152:155], v[80:95]
	v_mfma_f32_32x32x16_bf16 v[64:79], v[230:233], v[156:159], v[64:79]
	ds_read_b64_tr_b16 v[152:153], v249 offset:20480
	ds_read_b64_tr_b16 v[154:155], v249 offset:22528
	ds_read_b64_tr_b16 v[156:157], v249 offset:20992
	ds_read_b64_tr_b16 v[158:159], v249 offset:23040
	s_add_i32 s30, s85, s34
	s_add_i32 m0, s30, 0xc000
	s_nop 0
	global_load_lds_dwordx4 v246, s[2:3]
	s_waitcnt lgkmcnt(8)
	v_mfma_f32_32x32x16_bf16 v[80:95], v[234:237], v[238:241], v[80:95]
	v_mfma_f32_32x32x16_bf16 v[64:79], v[234:237], v[242:245], v[64:79]
	ds_read_b64_tr_b16 v[238:239], v249 offset:17408
	ds_read_b64_tr_b16 v[240:241], v249 offset:19456
	ds_read_b64_tr_b16 v[242:243], v249 offset:17920
	ds_read_b64_tr_b16 v[244:245], v249 offset:19968
	s_add_i32 s30, s85, s34
	s_add_i32 m0, s30, 0xe000
	s_nop 0
	global_load_lds_dwordx4 v247, s[2:3]
	s_waitcnt lgkmcnt(8)
	v_mfma_f32_32x32x16_bf16 v[32:47], v[230:233], v[144:147], v[32:47]
	v_mfma_f32_32x32x16_bf16 v[16:31], v[230:233], v[148:151], v[16:31]
	ds_read_b64_tr_b16 v[144:145], v249 offset:21504
	ds_read_b64_tr_b16 v[146:147], v249 offset:23552
	ds_read_b64_tr_b16 v[148:149], v249 offset:22016
	ds_read_b64_tr_b16 v[150:151], v249 offset:24064
	s_waitcnt lgkmcnt(8)
; #define SBAR() __builtin_amdgcn_sched_barrier(0)
; #define PVR(S, DA, DB, vbase) do { S[0] = tr_read<v_rd_off(DA, 0, 0)>(vbase); S[1] = tr_read<v_rd_off(DA, 0, 1)>(vbase); S[2] = tr_read<v_rd_off(DB, 0, 0)>(vbase); S[3] = tr_read<v_rd_off(DB, 0, 1)>(vbase); \
;     S[4] = tr_read<v_rd_off(DA, 1, 0)>(vbase); S[5] = tr_read<v_rd_off(DA, 1, 1)>(vbase); S[6] = tr_read<v_rd_off(DB, 1, 0)>(vbase); S[7] = tr_read<v_rd_off(DB, 1, 1)>(vbase); } while (0)
; #define RAWBAR() do { asm volatile("s_waitcnt lgkmcnt(0)" ::: "memory"); __builtin_amdgcn_s_barrier(); asm volatile("" ::: "memory"); } while (0)
; #define RAWBAR() do { asm volatile("s_waitcnt lgkmcnt(0)" ::: "memory"); __builtin_amdgcn_s_barrier(); asm volatile("" ::: "memory"); } while (0)
; #define RAWBAR() do { asm volatile("s_waitcnt lgkmcnt(0)" ::: "memory"); __builtin_amdgcn_s_barrier(); asm volatile("" ::: "memory"); } while (0)
; #define RAWBAR() do { asm volatile("s_waitcnt lgkmcnt(0)" ::: "memory"); __builtin_amdgcn_s_barrier(); asm volatile("" ::: "memory"); } while (0)
; #define RAWBAR() do { asm volatile("s_waitcnt lgkmcnt(0)" ::: "memory"); __builtin_amdgcn_s_barrier(); asm volatile("" ::: "memory"); } while (0)
; template <int MODE> ...
;     ...
;   for (int j = 0; j < NT; ++j) {
;     const int buf = j & 1;
;     if (j + 1 < NT) { STAGE((j + 1) * KVBLK, buf ^ 1); }
;     const char* Kb = K_lds + buf * 16384;
;     f32x16 pe = {}, po = {};
; #pragma unroll
;     for (int d0 = 0; d0 < 8; d0 += 2) {
;       const bf16x8 k0 = *reinterpret_cast<const bf16x8*>(Kb + KSWZ(krow, (d0 * 16 + hi * 8) * 2));
;       const bf16x8 k1 = *reinterpret_cast<const bf16x8*>(Kb + KSWZ(krow, ((d0 + 1) * 16 + hi * 8) * 2));
;       pe = __builtin_amdgcn_mfma_f32_32x32x16_bf16(k0, qr[d0], pe, 0, 0, 0);
;       po = __builtin_amdgcn_mfma_f32_32x32x16_bf16(k1, qr[d0 + 1], po, 0, 0, 0); }
;     const int vo = vb0 + buf * 32768;
;     s16x4 R0_[8], R1_[8];
;     PVR(R0_, 0, 1, vo);
;     f32x16 p;
; #pragma unroll
;     for (int r = 0; r < 16; ++r) p[r] = __builtin_amdgcn_exp2f(fmaf(pe[r] + po[r], C, negMc));
;     float ps = 0.f;
; #pragma unroll
;     for (int r = 0; r < 16; ++r) ps += p[r];
;     lsum += ps;
;     const bf16x8 own0 = pk8(p, 0), own1 = pk8(p, 8);
;     SBAR();
;     PV_TAIL4(o, vo, vo + 16384, own0, own1);
;     asm volatile("s_waitcnt vmcnt(0)" ::: "memory");
;     RAWBAR();
	v_mfma_f32_32x32x16_bf16 v[32:47], v[234:237], v[152:155], v[32:47]
	v_mfma_f32_32x32x16_bf16 v[16:31], v[234:237], v[156:159], v[16:31]
	s_waitcnt lgkmcnt(0)
	v_mfma_f32_32x32x16_bf16 v[48:63], v[230:233], v[238:241], v[48:63]
	v_mfma_f32_32x32x16_bf16 v[0:15], v[230:233], v[242:245], v[0:15]
	v_mfma_f32_32x32x16_bf16 v[48:63], v[234:237], v[144:147], v[48:63]
	v_mfma_f32_32x32x16_bf16 v[0:15], v[234:237], v[148:151], v[0:15]
	s_add_i32 s84, s84, 0x8000
	s_cmp_eq_u32 s84, 0x18000
	s_cselect_b32 s84, 0, s84
	ds_read_b128 v[230:233], v229 offset:0
	ds_read_b128 v[234:237], v228 offset:0
	ds_read_b128 v[238:241], v227 offset:0
	ds_read_b128 v[242:245], v226 offset:0
	v_exp_f32_e32 v128, v128
	v_exp_f32_e32 v129, v129
	v_exp_f32_e32 v130, v130
	v_exp_f32_e32 v131, v131
	s_waitcnt lgkmcnt(2)
	v_mfma_f32_32x32x16_bf16 v[144:159], v[230:233], v[188:191], 0
	v_mfma_f32_32x32x16_bf16 v[144:159], v[234:237], v[184:187], v[144:159]
	ds_read_b128 v[230:233], v229 offset:128
	ds_read_b128 v[234:237], v228 offset:128
	v_exp_f32_e32 v132, v132
	v_exp_f32_e32 v133, v133
	v_exp_f32_e32 v134, v134
	v_exp_f32_e32 v135, v135
	v_add_f32_e32 v250, v128, v129
	v_add_f32_e32 v250, v130, v250
	v_add_f32_e32 v250, v131, v250
	s_waitcnt lgkmcnt(2)
	v_mfma_f32_32x32x16_bf16 v[144:159], v[238:241], v[180:183], v[144:159]
	v_mfma_f32_32x32x16_bf16 v[144:159], v[242:245], v[176:179], v[144:159]
	ds_read_b128 v[238:241], v227 offset:128
	ds_read_b128 v[242:245], v226 offset:128
	v_exp_f32_e32 v136, v136
	v_exp_f32_e32 v137, v137
	v_exp_f32_e32 v138, v138
	v_exp_f32_e32 v139, v139
	v_add_f32_e32 v250, v132, v250
	v_add_f32_e32 v250, v133, v250
	v_add_f32_e32 v250, v134, v250
	v_add_f32_e32 v250, v135, v250
	s_waitcnt lgkmcnt(2)
	v_mfma_f32_32x32x16_bf16 v[144:159], v[230:233], v[172:175], v[144:159]
	v_mfma_f32_32x32x16_bf16 v[144:159], v[234:237], v[168:171], v[144:159]
	v_exp_f32_e32 v140, v140
	v_exp_f32_e32 v141, v141
	v_exp_f32_e32 v142, v142
	v_exp_f32_e32 v143, v143
	v_add_f32_e32 v250, v136, v250
	v_add_f32_e32 v250, v137, v250
	v_add_f32_e32 v250, v138, v250
	v_add_f32_e32 v250, v139, v250
	v_cvt_pk_bf16_f32 v230, v128, v129
	v_cvt_pk_bf16_f32 v231, v130, v131
	v_cvt_pk_bf16_f32 v232, v132, v133
	v_cvt_pk_bf16_f32 v233, v134, v135
	s_waitcnt lgkmcnt(0)
	v_mfma_f32_32x32x16_bf16 v[144:159], v[238:241], v[164:167], v[144:159]
	v_mfma_f32_32x32x16_bf16 v[144:159], v[242:245], v[160:163], v[144:159]
	s_waitcnt vmcnt(0)
	s_barrier
	s_add_u32 s86, s86, 0x4000
	s_addc_u32 s87, s87, 0
	s_add_u32 s2, s2, 0x8000
	s_addc_u32 s3, s3, 0
	s_mov_b32 m0, s34
	s_nop 0
	global_load_lds_dwordx4 v225, s[86:87]
	s_add_i32 m0, s34, 0x2000
	s_nop 0
	global_load_lds_dwordx4 v223, s[86:87]
	v_add_u32_e32 v249, s84, v218
	s_sub_u32 s85, s84, 0x8000
	s_cmp_eq_u32 s84, 0
	s_cselect_b32 s85, 0x10000, s85
	ds_read_b64_tr_b16 v[238:239], v249 offset:0
	ds_read_b64_tr_b16 v[240:241], v249 offset:2048
	ds_read_b64_tr_b16 v[242:243], v249 offset:512
	ds_read_b64_tr_b16 v[244:245], v249 offset:2560
	v_permlane32_swap_b32_e32 v230, v232
	v_permlane32_swap_b32_e32 v231, v233
	ds_read_b64_tr_b16 v[128:129], v249 offset:4096
	ds_read_b64_tr_b16 v[130:131], v249 offset:6144
	ds_read_b64_tr_b16 v[132:133], v249 offset:4608
	ds_read_b64_tr_b16 v[134:135], v249 offset:6656
	v_add_f32_e32 v250, v140, v250
	v_add_f32_e32 v250, v141, v250
	v_add_f32_e32 v250, v142, v250
	v_add_f32_e32 v250, v143, v250
	v_cvt_pk_bf16_f32 v234, v136, v137
	v_cvt_pk_bf16_f32 v235, v138, v139
	v_cvt_pk_bf16_f32 v236, v140, v141
	v_cvt_pk_bf16_f32 v237, v142, v143
	v_add_f32_e32 v219, v219, v250
	ds_read_b64_tr_b16 v[136:137], v249 offset:1024
	ds_read_b64_tr_b16 v[138:139], v249 offset:3072
	ds_read_b64_tr_b16 v[140:141], v249 offset:1536
	ds_read_b64_tr_b16 v[142:143], v249 offset:3584
	v_permlane32_swap_b32_e32 v234, v236
	v_permlane32_swap_b32_e32 v235, v237
	s_waitcnt lgkmcnt(8)
	v_mfma_f32_32x32x16_bf16 v[112:127], v[230:233], v[238:241], v[112:127]
	v_mfma_f32_32x32x16_bf16 v[96:111], v[230:233], v[242:245], v[96:111]
	ds_read_b64_tr_b16 v[238:239], v249 offset:5120
	ds_read_b64_tr_b16 v[240:241], v249 offset:7168
	ds_read_b64_tr_b16 v[242:243], v249 offset:5632
	ds_read_b64_tr_b16 v[244:245], v249 offset:7680
	s_add_i32 s30, s85, s34
	s_add_i32 m0, s30, 0x8000
	s_nop 0
	global_load_lds_dwordx4 v222, s[2:3]
	s_waitcnt lgkmcnt(8)
	v_mfma_f32_32x32x16_bf16 v[112:127], v[234:237], v[128:131], v[112:127]
	v_mfma_f32_32x32x16_bf16 v[96:111], v[234:237], v[132:135], v[96:111]
	ds_read_b64_tr_b16 v[128:129], v249 offset:16384
	ds_read_b64_tr_b16 v[130:131], v249 offset:18432
	ds_read_b64_tr_b16 v[132:133], v249 offset:16896
	ds_read_b64_tr_b16 v[134:135], v249 offset:18944
	s_add_i32 s30, s85, s34
	s_add_i32 m0, s30, 0xa000
	s_nop 0
	global_load_lds_dwordx4 v221, s[2:3]
	s_waitcnt lgkmcnt(8)
	v_mfma_f32_32x32x16_bf16 v[80:95], v[230:233], v[136:139], v[80:95]
	v_mfma_f32_32x32x16_bf16 v[64:79], v[230:233], v[140:143], v[64:79]
	ds_read_b64_tr_b16 v[136:137], v249 offset:20480
	ds_read_b64_tr_b16 v[138:139], v249 offset:22528
	ds_read_b64_tr_b16 v[140:141], v249 offset:20992
	ds_read_b64_tr_b16 v[142:143], v249 offset:23040
	s_add_i32 s30, s85, s34
	s_add_i32 m0, s30, 0xc000
	s_nop 0
	global_load_lds_dwordx4 v246, s[2:3]
	s_waitcnt lgkmcnt(8)
	v_mfma_f32_32x32x16_bf16 v[80:95], v[234:237], v[238:241], v[80:95]
	v_mfma_f32_32x32x16_bf16 v[64:79], v[234:237], v[242:245], v[64:79]
	ds_read_b64_tr_b16 v[238:239], v249 offset:17408
	ds_read_b64_tr_b16 v[240:241], v249 offset:19456
	ds_read_b64_tr_b16 v[242:243], v249 offset:17920
	ds_read_b64_tr_b16 v[244:245], v249 offset:19968
	s_add_i32 s30, s85, s34
	s_add_i32 m0, s30, 0xe000
	s_nop 0
	global_load_lds_dwordx4 v247, s[2:3]
	s_waitcnt lgkmcnt(8)
	v_mfma_f32_32x32x16_bf16 v[32:47], v[230:233], v[128:131], v[32:47]
	v_mfma_f32_32x32x16_bf16 v[16:31], v[230:233], v[132:135], v[16:31]
	ds_read_b64_tr_b16 v[128:129], v249 offset:21504
	ds_read_b64_tr_b16 v[130:131], v249 offset:23552
	ds_read_b64_tr_b16 v[132:133], v249 offset:22016
	ds_read_b64_tr_b16 v[134:135], v249 offset:24064
	s_waitcnt lgkmcnt(8)
	v_mfma_f32_32x32x16_bf16 v[32:47], v[234:237], v[136:139], v[32:47]
	v_mfma_f32_32x32x16_bf16 v[16:31], v[234:237], v[140:143], v[16:31]
	s_waitcnt lgkmcnt(0)
	v_mfma_f32_32x32x16_bf16 v[48:63], v[230:233], v[238:241], v[48:63]
	v_mfma_f32_32x32x16_bf16 v[0:15], v[230:233], v[242:245], v[0:15]
	v_mfma_f32_32x32x16_bf16 v[48:63], v[234:237], v[128:131], v[48:63]
	v_mfma_f32_32x32x16_bf16 v[0:15], v[234:237], v[132:135], v[0:15]
	s_add_i32 s84, s84, 0x8000
	s_cmp_eq_u32 s84, 0x18000
	s_cselect_b32 s84, 0, s84
	s_add_i32 s40, s40, 1
	s_cmpk_eq_i32 s40, 0x82
	s_cbranch_scc0 .LattnB_m1
	s_waitcnt vmcnt(0)
	s_barrier
